# speedup vs baseline: 1.0051x; 1.0051x over previous
; #define STAGE_A(bufoff, gbase) STAGEX(bufoff, gbase, voffA)
; #define STAGE_B(bufoff, gbase) STAGEX(bufoff, gbase, voffB)
; #define LDA(dst, b, h) do { _Pragma("unroll") for (int m = 0; m < 4; ++m) _Pragma("unroll") for (int k = 0; k < 2; ++k) dst[m][k] = *(const __attribute__((address_space(3))) bf16x8*)(lds + SA(b, h) + aoff + m * 2048 + k * 1024); } while (0)
; #define LDB(dst, b, h) do { _Pragma("unroll") for (int n = 0; n < 2; ++n) _Pragma("unroll") for (int k = 0; k < 2; ++k) dst[n][k] = *(const __attribute__((address_space(3))) bf16x8*)(lds + SB_(b, h) + boff + n * 2048 + k * 1024); } while (0)
; #define MMA(ai, bj, At, Bt_) do { __builtin_amdgcn_s_setprio(1); _Pragma("unroll") for (int m = 0; m < 4; ++m) _Pragma("unroll") for (int n = 0; n < 2; ++n) _Pragma("unroll") for (int k = 0; k < 2; ++k) \
;       acc[ai][bj][m][n] = __builtin_amdgcn_mfma_f32_16x16x32_bf16(Bt_[n][k], At[m][k], acc[ai][bj][m][n], 0, 0, 0); \
;     __builtin_amdgcn_s_setprio(0); } while (0)
; #define WAIT_V(n) asm volatile("s_waitcnt vmcnt(" #n ")" ::: "memory")
; #define WAIT_L(n) asm volatile("s_waitcnt lgkmcnt(" #n ")" ::: "memory")
; #define BAR __builtin_amdgcn_s_barrier()
; #define SCHED __builtin_amdgcn_sched_barrier(0)
; template <int MODE>
; DEV void gemm_phase(const bf16_t* __restrict__ A, const bf16_t* __restrict__ Bt, int M, int N, int K, bf16_t* __restrict__ Out, int ldo,
;                     const float* __restrict__ rstd, const float* __restrict__ rope) {
;     ...
;     for (int t = 0; t < nt; t += 2) {
;       const bool last = (t == nt - 2);
;       const char* a1 = cA + (size_t)(t + 1) * 128;
;       const char* a2 = last ? nA : cA + (size_t)(t + 2) * 128; const char* b2 = last ? nB : cB + (size_t)(t + 2) * 128;
;       const char* a3 = a2 + 128; const char* b3 = b2 + 128;
;       LDB(B0, 0, 0); LDB(B1, 0, 1); SCHED; LDA(At, 0, 0); STAGE_A(SA(1, 1), a1 + hstep);
;       WAIT_V(8); WAIT_L(0); BAR; MMA(0, 0, At, B0); MMA(0, 1, At, B1); BAR; SCHED;
;       LDA(At, 0, 1); STAGE_B(SB_(0, 0), b2); STAGE_B(SB_(0, 1), b2 + hstep); STAGE_A(SA(0, 0), a2);
.LBB0_128:
	s_add_u32 s26, s44, s8
	s_addc_u32 s27, s45, s9
	s_add_u32 s26, s26, 0x12200100
	s_addc_u32 s27, s27, 0
	s_add_u32 s49, s46, s8
	s_addc_u32 s50, s47, s9
	s_add_i32 s51, 0, 0x10000
	s_cmpk_eq_i32 s8, 0xf00
	s_cselect_b32 s29, s42, s27
	s_cselect_b32 s28, s19, s26
	s_cselect_b32 s27, s43, s50
	s_cselect_b32 s26, s21, s49
	s_add_i32 s49, 0, 0x14000
	v_add_u32_e32 v144, s51, v171
	v_add_u32_e32 v168, s49, v171
	ds_read_b128 v[132:135], v144
	ds_read_b128 v[136:139], v144 offset:1024
	ds_read_b128 v[140:143], v144 offset:2048
	ds_read_b128 v[144:147], v144 offset:3072
	ds_read_b128 v[148:151], v168
	ds_read_b128 v[164:167], v168 offset:1024
	ds_read_b128 v[174:177], v168 offset:2048
	ds_read_b128 v[178:181], v168 offset:3072
	v_lshl_add_u64 v[168:169], v[128:129], 0, s[8:9]
	s_add_i32 m0, s31, 0xc000
	ds_read_b128 v[182:185], v172
	ds_read_b128 v[186:189], v172 offset:1024
	ds_read_b128 v[194:197], v172 offset:2048
	ds_read_b128 v[198:201], v172 offset:3072
	ds_read_b128 v[202:205], v172 offset:4096
	ds_read_b128 v[206:209], v172 offset:5120
	ds_read_b128 v[216:219], v172 offset:6144
	ds_read_b128 v[220:223], v172 offset:7168
	global_load_lds_dwordx4 v[168:169], off
	v_lshl_add_u64 v[168:169], v[130:131], 0, s[8:9]
	s_add_i32 m0, s31, 0xe000
	s_nop 0
	global_load_lds_dwordx4 v[168:169], off
	s_waitcnt vmcnt(8)
	s_waitcnt lgkmcnt(0)
	s_barrier
	s_setprio 1
	s_waitcnt lgkmcnt(0)
	v_mfma_f32_16x16x32_bf16 v[124:127], v[132:135], v[182:185], v[124:127]
	v_mfma_f32_16x16x32_bf16 v[120:123], v[140:143], v[182:185], v[120:123]
	v_mfma_f32_16x16x32_bf16 v[108:111], v[132:135], v[194:197], v[108:111]
	v_mfma_f32_16x16x32_bf16 v[104:107], v[140:143], v[194:197], v[104:107]
	v_mfma_f32_16x16x32_bf16 v[92:95], v[132:135], v[202:205], v[92:95]
	v_mfma_f32_16x16x32_bf16 v[88:91], v[140:143], v[202:205], v[88:91]
	v_mfma_f32_16x16x32_bf16 v[76:79], v[132:135], v[216:219], v[76:79]
	v_mfma_f32_16x16x32_bf16 v[72:75], v[140:143], v[216:219], v[72:75]
	v_mfma_f32_16x16x32_bf16 v[124:127], v[136:139], v[186:189], v[124:127]
	v_mfma_f32_16x16x32_bf16 v[120:123], v[144:147], v[186:189], v[120:123]
	v_mfma_f32_16x16x32_bf16 v[108:111], v[136:139], v[198:201], v[108:111]
	v_mfma_f32_16x16x32_bf16 v[104:107], v[144:147], v[198:201], v[104:107]
	v_mfma_f32_16x16x32_bf16 v[92:95], v[136:139], v[206:209], v[92:95]
	v_mfma_f32_16x16x32_bf16 v[88:91], v[144:147], v[206:209], v[88:91]
	v_mfma_f32_16x16x32_bf16 v[76:79], v[136:139], v[220:223], v[76:79]
	v_mfma_f32_16x16x32_bf16 v[72:75], v[144:147], v[220:223], v[72:75]
	v_mfma_f32_16x16x32_bf16 v[116:119], v[148:151], v[182:185], v[116:119]
	v_mfma_f32_16x16x32_bf16 v[112:115], v[174:177], v[182:185], v[112:115]
	v_mfma_f32_16x16x32_bf16 v[100:103], v[148:151], v[194:197], v[100:103]
	v_mfma_f32_16x16x32_bf16 v[96:99], v[174:177], v[194:197], v[96:99]
	v_mfma_f32_16x16x32_bf16 v[84:87], v[148:151], v[202:205], v[84:87]
	v_mfma_f32_16x16x32_bf16 v[80:83], v[174:177], v[202:205], v[80:83]
	v_mfma_f32_16x16x32_bf16 v[68:71], v[148:151], v[216:219], v[68:71]
	v_mfma_f32_16x16x32_bf16 v[64:67], v[174:177], v[216:219], v[64:67]
	v_mfma_f32_16x16x32_bf16 v[116:119], v[164:167], v[186:189], v[116:119]
	v_mfma_f32_16x16x32_bf16 v[112:115], v[178:181], v[186:189], v[112:115]
	v_mfma_f32_16x16x32_bf16 v[100:103], v[164:167], v[198:201], v[100:103]
	v_mfma_f32_16x16x32_bf16 v[96:99], v[178:181], v[198:201], v[96:99]
	v_mfma_f32_16x16x32_bf16 v[84:87], v[164:167], v[206:209], v[84:87]
	v_mfma_f32_16x16x32_bf16 v[80:83], v[178:181], v[206:209], v[80:83]
	v_mfma_f32_16x16x32_bf16 v[68:71], v[164:167], v[220:223], v[68:71]
	v_mfma_f32_16x16x32_bf16 v[64:67], v[178:181], v[220:223], v[64:67]
	s_setprio 0
	s_barrier
	s_add_i32 s50, s51, s30
	v_lshl_add_u64 v[168:169], s[26:27], 0, v[192:193]
	s_mov_b32 m0, s50
	ds_read_b128 v[182:185], v172 offset:16384
	ds_read_b128 v[186:189], v172 offset:17408
	ds_read_b128 v[194:197], v172 offset:18432
	ds_read_b128 v[198:201], v172 offset:19456
	ds_read_b128 v[202:205], v172 offset:20480
	ds_read_b128 v[206:209], v172 offset:21504
	ds_read_b128 v[216:219], v172 offset:22528
	ds_read_b128 v[220:223], v172 offset:23552
	global_load_lds_dwordx4 v[168:169], off
	s_add_i32 m0, s50, 0x2000
	s_add_u32 s50, s26, 0x80000
	v_lshl_add_u64 v[190:191], s[26:27], 0, v[152:153]
	s_addc_u32 s51, s27, 0
	s_add_i32 s49, s49, s30
	global_load_lds_dwordx4 v[190:191], off
	v_lshl_add_u64 v[212:213], s[50:51], 0, v[192:193]
	s_mov_b32 m0, s49
	v_lshl_add_u64 v[214:215], s[28:29], 0, v[154:155]
	global_load_lds_dwordx4 v[212:213], off
	v_lshl_add_u64 v[212:213], s[50:51], 0, v[152:153]
	s_add_i32 m0, s49, 0x2000
	s_nop 0
	global_load_lds_dwordx4 v[212:213], off
	v_lshl_add_u64 v[212:213], s[28:29], 0, v[156:157]
	s_mov_b32 m0, s31
	s_nop 0
	global_load_lds_dwordx4 v[212:213], off
	s_mov_b32 m0, s34
	s_nop 0
	global_load_lds_dwordx4 v[214:215], off
	s_waitcnt vmcnt(8)
	s_waitcnt lgkmcnt(0)
	s_barrier
; #define STAGE_A(bufoff, gbase) STAGEX(bufoff, gbase, voffA)
; #define LDA(dst, b, h) do { _Pragma("unroll") for (int m = 0; m < 4; ++m) _Pragma("unroll") for (int k = 0; k < 2; ++k) dst[m][k] = *(const __attribute__((address_space(3))) bf16x8*)(lds + SA(b, h) + aoff + m * 2048 + k * 1024); } while (0)
; #define LDB(dst, b, h) do { _Pragma("unroll") for (int n = 0; n < 2; ++n) _Pragma("unroll") for (int k = 0; k < 2; ++k) dst[n][k] = *(const __attribute__((address_space(3))) bf16x8*)(lds + SB_(b, h) + boff + n * 2048 + k * 1024); } while (0)
; #define MMA(ai, bj, At, Bt_) do { __builtin_amdgcn_s_setprio(1); _Pragma("unroll") for (int m = 0; m < 4; ++m) _Pragma("unroll") for (int n = 0; n < 2; ++n) _Pragma("unroll") for (int k = 0; k < 2; ++k) \
;       acc[ai][bj][m][n] = __builtin_amdgcn_mfma_f32_16x16x32_bf16(Bt_[n][k], At[m][k], acc[ai][bj][m][n], 0, 0, 0); \
;     __builtin_amdgcn_s_setprio(0); } while (0)
; #define WAIT_V(n) asm volatile("s_waitcnt vmcnt(" #n ")" ::: "memory")
; #define WAIT_L(n) asm volatile("s_waitcnt lgkmcnt(" #n ")" ::: "memory")
; #define BAR __builtin_amdgcn_s_barrier()
; #define SCHED __builtin_amdgcn_sched_barrier(0)
; template <int MODE>
; DEV void gemm_phase(const bf16_t* __restrict__ A, const bf16_t* __restrict__ Bt, int M, int N, int K, bf16_t* __restrict__ Out, int ldo,
;                     const float* __restrict__ rstd, const float* __restrict__ rope) {
;     ...
;       WAIT_V(8); WAIT_L(0); BAR; MMA(1, 0, At, B0); MMA(1, 1, At, B1); BAR; SCHED;
;       LDB(B0, 1, 0); LDB(B1, 1, 1); SCHED; LDA(At, 1, 0); STAGE_A(SA(0, 1), a2 + hstep);
;       WAIT_V(8); WAIT_L(0); BAR; MMA(0, 0, At, B0); MMA(0, 1, At, B1); BAR; SCHED;
	s_setprio 1
	s_waitcnt lgkmcnt(0)
	v_mfma_f32_16x16x32_bf16 v[60:63], v[132:135], v[182:185], v[60:63]
	v_mfma_f32_16x16x32_bf16 v[56:59], v[140:143], v[182:185], v[56:59]
	v_mfma_f32_16x16x32_bf16 v[44:47], v[132:135], v[194:197], v[44:47]
	v_mfma_f32_16x16x32_bf16 v[40:43], v[140:143], v[194:197], v[40:43]
	v_mfma_f32_16x16x32_bf16 v[28:31], v[132:135], v[202:205], v[28:31]
	v_mfma_f32_16x16x32_bf16 v[24:27], v[140:143], v[202:205], v[24:27]
	v_mfma_f32_16x16x32_bf16 v[12:15], v[132:135], v[216:219], v[12:15]
	v_mfma_f32_16x16x32_bf16 v[8:11], v[140:143], v[216:219], v[8:11]
	v_mfma_f32_16x16x32_bf16 v[60:63], v[136:139], v[186:189], v[60:63]
	v_mfma_f32_16x16x32_bf16 v[56:59], v[144:147], v[186:189], v[56:59]
	v_mfma_f32_16x16x32_bf16 v[44:47], v[136:139], v[198:201], v[44:47]
	v_mfma_f32_16x16x32_bf16 v[40:43], v[144:147], v[198:201], v[40:43]
	v_mfma_f32_16x16x32_bf16 v[28:31], v[136:139], v[206:209], v[28:31]
	v_mfma_f32_16x16x32_bf16 v[24:27], v[144:147], v[206:209], v[24:27]
	v_mfma_f32_16x16x32_bf16 v[12:15], v[136:139], v[220:223], v[12:15]
	v_mfma_f32_16x16x32_bf16 v[8:11], v[144:147], v[220:223], v[8:11]
	v_mfma_f32_16x16x32_bf16 v[52:55], v[148:151], v[182:185], v[52:55]
	v_mfma_f32_16x16x32_bf16 v[48:51], v[174:177], v[182:185], v[48:51]
	v_mfma_f32_16x16x32_bf16 v[36:39], v[148:151], v[194:197], v[36:39]
	v_mfma_f32_16x16x32_bf16 v[32:35], v[174:177], v[194:197], v[32:35]
	v_mfma_f32_16x16x32_bf16 v[20:23], v[148:151], v[202:205], v[20:23]
	v_mfma_f32_16x16x32_bf16 v[16:19], v[174:177], v[202:205], v[16:19]
	v_mfma_f32_16x16x32_bf16 v[4:7], v[148:151], v[216:219], v[4:7]
	v_mfma_f32_16x16x32_bf16 v[0:3], v[174:177], v[216:219], v[0:3]
	v_mfma_f32_16x16x32_bf16 v[52:55], v[164:167], v[186:189], v[52:55]
	v_mfma_f32_16x16x32_bf16 v[48:51], v[178:181], v[186:189], v[48:51]
	v_mfma_f32_16x16x32_bf16 v[36:39], v[164:167], v[198:201], v[36:39]
	v_mfma_f32_16x16x32_bf16 v[32:35], v[178:181], v[198:201], v[32:35]
	v_mfma_f32_16x16x32_bf16 v[20:23], v[164:167], v[206:209], v[20:23]
	v_mfma_f32_16x16x32_bf16 v[16:19], v[178:181], v[206:209], v[16:19]
	v_mfma_f32_16x16x32_bf16 v[4:7], v[164:167], v[220:223], v[4:7]
	v_mfma_f32_16x16x32_bf16 v[0:3], v[178:181], v[220:223], v[0:3]
	s_setprio 0
	s_barrier
	s_add_i32 s49, 0, 0x18000
	s_add_i32 s50, 0, 0x1c000
	v_add_u32_e32 v144, s49, v171
	v_add_u32_e32 v173, s50, v171
	ds_read_b128 v[132:135], v144
	ds_read_b128 v[136:139], v144 offset:1024
	ds_read_b128 v[140:143], v144 offset:2048
	ds_read_b128 v[144:147], v144 offset:3072
	ds_read_b128 v[148:151], v173
	ds_read_b128 v[164:167], v173 offset:1024
	ds_read_b128 v[174:177], v173 offset:2048
	ds_read_b128 v[178:181], v173 offset:3072
	s_add_u32 s28, s28, 0x80000
	s_addc_u32 s29, s29, 0
	s_mov_b32 m0, s35
	v_lshl_add_u64 v[224:225], s[28:29], 0, v[156:157]
	ds_read_b128 v[182:185], v172 offset:32768
	ds_read_b128 v[186:189], v172 offset:33792
	ds_read_b128 v[194:197], v172 offset:34816
	ds_read_b128 v[198:201], v172 offset:35840
	ds_read_b128 v[202:205], v172 offset:36864
	ds_read_b128 v[206:209], v172 offset:37888
	ds_read_b128 v[216:219], v172 offset:38912
	ds_read_b128 v[220:223], v172 offset:39936
	global_load_lds_dwordx4 v[224:225], off
	v_lshl_add_u64 v[224:225], s[28:29], 0, v[154:155]
	s_mov_b32 m0, s36
	s_nop 0
	global_load_lds_dwordx4 v[224:225], off
	s_waitcnt vmcnt(8)
	s_waitcnt lgkmcnt(0)
	s_barrier
	s_setprio 1
	s_waitcnt lgkmcnt(0)
	v_mfma_f32_16x16x32_bf16 v[124:127], v[132:135], v[182:185], v[124:127]
	v_mfma_f32_16x16x32_bf16 v[120:123], v[140:143], v[182:185], v[120:123]
	v_mfma_f32_16x16x32_bf16 v[108:111], v[132:135], v[194:197], v[108:111]
	v_mfma_f32_16x16x32_bf16 v[104:107], v[140:143], v[194:197], v[104:107]
	v_mfma_f32_16x16x32_bf16 v[92:95], v[132:135], v[202:205], v[92:95]
	v_mfma_f32_16x16x32_bf16 v[88:91], v[140:143], v[202:205], v[88:91]
	v_mfma_f32_16x16x32_bf16 v[76:79], v[132:135], v[216:219], v[76:79]
	v_mfma_f32_16x16x32_bf16 v[72:75], v[140:143], v[216:219], v[72:75]
	v_mfma_f32_16x16x32_bf16 v[124:127], v[136:139], v[186:189], v[124:127]
	v_mfma_f32_16x16x32_bf16 v[120:123], v[144:147], v[186:189], v[120:123]
	v_mfma_f32_16x16x32_bf16 v[108:111], v[136:139], v[198:201], v[108:111]
	v_mfma_f32_16x16x32_bf16 v[104:107], v[144:147], v[198:201], v[104:107]
	v_mfma_f32_16x16x32_bf16 v[92:95], v[136:139], v[206:209], v[92:95]
	v_mfma_f32_16x16x32_bf16 v[88:91], v[144:147], v[206:209], v[88:91]
	v_mfma_f32_16x16x32_bf16 v[76:79], v[136:139], v[220:223], v[76:79]
	v_mfma_f32_16x16x32_bf16 v[72:75], v[144:147], v[220:223], v[72:75]
	v_mfma_f32_16x16x32_bf16 v[116:119], v[148:151], v[182:185], v[116:119]
	v_mfma_f32_16x16x32_bf16 v[112:115], v[174:177], v[182:185], v[112:115]
	v_mfma_f32_16x16x32_bf16 v[100:103], v[148:151], v[194:197], v[100:103]
	v_mfma_f32_16x16x32_bf16 v[96:99], v[174:177], v[194:197], v[96:99]
	v_mfma_f32_16x16x32_bf16 v[84:87], v[148:151], v[202:205], v[84:87]
	v_mfma_f32_16x16x32_bf16 v[80:83], v[174:177], v[202:205], v[80:83]
	v_mfma_f32_16x16x32_bf16 v[68:71], v[148:151], v[216:219], v[68:71]
	v_mfma_f32_16x16x32_bf16 v[64:67], v[174:177], v[216:219], v[64:67]
	v_mfma_f32_16x16x32_bf16 v[116:119], v[164:167], v[186:189], v[116:119]
	v_mfma_f32_16x16x32_bf16 v[112:115], v[178:181], v[186:189], v[112:115]
	v_mfma_f32_16x16x32_bf16 v[100:103], v[164:167], v[198:201], v[100:103]
	v_mfma_f32_16x16x32_bf16 v[96:99], v[178:181], v[198:201], v[96:99]
	v_mfma_f32_16x16x32_bf16 v[84:87], v[164:167], v[206:209], v[84:87]
	v_mfma_f32_16x16x32_bf16 v[80:83], v[178:181], v[206:209], v[80:83]
	v_mfma_f32_16x16x32_bf16 v[68:71], v[164:167], v[220:223], v[68:71]
	v_mfma_f32_16x16x32_bf16 v[64:67], v[178:181], v[220:223], v[64:67]
	s_setprio 0
	s_barrier
; #define STAGE_A(bufoff, gbase) STAGEX(bufoff, gbase, voffA)
; #define STAGE_B(bufoff, gbase) STAGEX(bufoff, gbase, voffB)
; #define LDA(dst, b, h) do { _Pragma("unroll") for (int m = 0; m < 4; ++m) _Pragma("unroll") for (int k = 0; k < 2; ++k) dst[m][k] = *(const __attribute__((address_space(3))) bf16x8*)(lds + SA(b, h) + aoff + m * 2048 + k * 1024); } while (0)
; #define MMA(ai, bj, At, Bt_) do { __builtin_amdgcn_s_setprio(1); _Pragma("unroll") for (int m = 0; m < 4; ++m) _Pragma("unroll") for (int n = 0; n < 2; ++n) _Pragma("unroll") for (int k = 0; k < 2; ++k) \
;       acc[ai][bj][m][n] = __builtin_amdgcn_mfma_f32_16x16x32_bf16(Bt_[n][k], At[m][k], acc[ai][bj][m][n], 0, 0, 0); \
;     __builtin_amdgcn_s_setprio(0); } while (0)
; #define WAIT_V(n) asm volatile("s_waitcnt vmcnt(" #n ")" ::: "memory")
; #define WAIT_L(n) asm volatile("s_waitcnt lgkmcnt(" #n ")" ::: "memory")
; #define BAR __builtin_amdgcn_s_barrier()
; #define SCHED __builtin_amdgcn_sched_barrier(0)
; template <int MODE>
; DEV void gemm_phase(const bf16_t* __restrict__ A, const bf16_t* __restrict__ Bt, int M, int N, int K, bf16_t* __restrict__ Out, int ldo,
;                     const float* __restrict__ rstd, const float* __restrict__ rope) {
;     ...
;       LDA(At, 1, 1); STAGE_B(SB_(1, 0), b3); STAGE_B(SB_(1, 1), b3 + hstep); STAGE_A(SA(1, 0), a3);
;       WAIT_V(8); WAIT_L(0); BAR; MMA(1, 0, At, B0); MMA(1, 1, At, B1); BAR; SCHED;
;     }
	s_add_i32 s28, s49, s30
	v_lshl_add_u64 v[168:169], v[168:169], 0, s[88:89]
	s_mov_b32 m0, s28
	ds_read_b128 v[182:185], v172 offset:49152
	ds_read_b128 v[186:189], v172 offset:50176
	ds_read_b128 v[194:197], v172 offset:51200
	ds_read_b128 v[198:201], v172 offset:52224
	ds_read_b128 v[202:205], v172 offset:53248
	ds_read_b128 v[206:209], v172 offset:54272
	ds_read_b128 v[216:219], v172 offset:55296
	ds_read_b128 v[220:223], v172 offset:56320
	global_load_lds_dwordx4 v[168:169], off
	s_add_i32 m0, s28, 0x2000
	s_add_u32 s26, s26, 0x80080
	v_lshl_add_u64 v[168:169], v[190:191], 0, s[88:89]
	s_addc_u32 s27, s27, 0
	s_add_i32 s28, s50, s30
	global_load_lds_dwordx4 v[168:169], off
	v_lshl_add_u64 v[168:169], s[26:27], 0, v[192:193]
	s_mov_b32 m0, s28
	s_nop 0
	global_load_lds_dwordx4 v[168:169], off
	v_lshl_add_u64 v[168:169], s[26:27], 0, v[152:153]
	s_add_i32 m0, s28, 0x2000
	s_nop 0
	global_load_lds_dwordx4 v[168:169], off
	v_lshl_add_u64 v[168:169], v[212:213], 0, s[88:89]
	s_mov_b32 m0, s37
	s_nop 0
	global_load_lds_dwordx4 v[168:169], off
	v_lshl_add_u64 v[168:169], v[214:215], 0, s[88:89]
	s_mov_b32 m0, s38
	s_nop 0
	global_load_lds_dwordx4 v[168:169], off
	s_waitcnt vmcnt(8)
	s_waitcnt lgkmcnt(0)
	s_barrier
	s_setprio 1
	s_waitcnt lgkmcnt(0)
	v_mfma_f32_16x16x32_bf16 v[60:63], v[132:135], v[182:185], v[60:63]
	v_mfma_f32_16x16x32_bf16 v[56:59], v[140:143], v[182:185], v[56:59]
	v_mfma_f32_16x16x32_bf16 v[44:47], v[132:135], v[194:197], v[44:47]
	v_mfma_f32_16x16x32_bf16 v[40:43], v[140:143], v[194:197], v[40:43]
	v_mfma_f32_16x16x32_bf16 v[28:31], v[132:135], v[202:205], v[28:31]
	v_mfma_f32_16x16x32_bf16 v[24:27], v[140:143], v[202:205], v[24:27]
	v_mfma_f32_16x16x32_bf16 v[12:15], v[132:135], v[216:219], v[12:15]
	v_mfma_f32_16x16x32_bf16 v[8:11], v[140:143], v[216:219], v[8:11]
	v_mfma_f32_16x16x32_bf16 v[60:63], v[136:139], v[186:189], v[60:63]
	v_mfma_f32_16x16x32_bf16 v[56:59], v[144:147], v[186:189], v[56:59]
	v_mfma_f32_16x16x32_bf16 v[44:47], v[136:139], v[198:201], v[44:47]
	v_mfma_f32_16x16x32_bf16 v[40:43], v[144:147], v[198:201], v[40:43]
	v_mfma_f32_16x16x32_bf16 v[28:31], v[136:139], v[206:209], v[28:31]
	v_mfma_f32_16x16x32_bf16 v[24:27], v[144:147], v[206:209], v[24:27]
	v_mfma_f32_16x16x32_bf16 v[12:15], v[136:139], v[220:223], v[12:15]
	v_mfma_f32_16x16x32_bf16 v[8:11], v[144:147], v[220:223], v[8:11]
	v_mfma_f32_16x16x32_bf16 v[52:55], v[148:151], v[182:185], v[52:55]
	v_mfma_f32_16x16x32_bf16 v[48:51], v[174:177], v[182:185], v[48:51]
	v_mfma_f32_16x16x32_bf16 v[36:39], v[148:151], v[194:197], v[36:39]
	v_mfma_f32_16x16x32_bf16 v[32:35], v[174:177], v[194:197], v[32:35]
	v_mfma_f32_16x16x32_bf16 v[20:23], v[148:151], v[202:205], v[20:23]
	v_mfma_f32_16x16x32_bf16 v[16:19], v[174:177], v[202:205], v[16:19]
	v_mfma_f32_16x16x32_bf16 v[4:7], v[148:151], v[216:219], v[4:7]
	v_mfma_f32_16x16x32_bf16 v[0:3], v[174:177], v[216:219], v[0:3]
	v_mfma_f32_16x16x32_bf16 v[52:55], v[164:167], v[186:189], v[52:55]
	v_mfma_f32_16x16x32_bf16 v[48:51], v[178:181], v[186:189], v[48:51]
	v_mfma_f32_16x16x32_bf16 v[36:39], v[164:167], v[198:201], v[36:39]
	v_mfma_f32_16x16x32_bf16 v[32:35], v[178:181], v[198:201], v[32:35]
	v_mfma_f32_16x16x32_bf16 v[20:23], v[164:167], v[206:209], v[20:23]
	v_mfma_f32_16x16x32_bf16 v[16:19], v[178:181], v[206:209], v[16:19]
	v_mfma_f32_16x16x32_bf16 v[4:7], v[164:167], v[220:223], v[4:7]
	v_mfma_f32_16x16x32_bf16 v[0:3], v[178:181], v[220:223], v[0:3]
	s_setprio 0
	s_barrier
	s_add_i32 s48, s48, 2
	s_add_u32 s8, s8, 0x100
	s_addc_u32 s9, s9, 0
	s_cmp_gt_u32 s48, 29
	s_cbranch_scc0 .LBB0_128
	s_and_b64 vcc, exec, s[12:13]
	s_cbranch_vccz .LBB0_131
	s_barrier

; #define STAGE_A(bufoff, gbase) STAGEX(bufoff, gbase, voffA)
; #define STAGE_B(bufoff, gbase) STAGEX(bufoff, gbase, voffB)
; #define LDA(dst, b, h) do { _Pragma("unroll") for (int m = 0; m < 4; ++m) _Pragma("unroll") for (int k = 0; k < 2; ++k) dst[m][k] = *(const __attribute__((address_space(3))) bf16x8*)(lds + SA(b, h) + aoff + m * 2048 + k * 1024); } while (0)
; #define LDB(dst, b, h) do { _Pragma("unroll") for (int n = 0; n < 2; ++n) _Pragma("unroll") for (int k = 0; k < 2; ++k) dst[n][k] = *(const __attribute__((address_space(3))) bf16x8*)(lds + SB_(b, h) + boff + n * 2048 + k * 1024); } while (0)
; #define MMA(ai, bj, At, Bt_) do { __builtin_amdgcn_s_setprio(1); _Pragma("unroll") for (int m = 0; m < 4; ++m) _Pragma("unroll") for (int n = 0; n < 2; ++n) _Pragma("unroll") for (int k = 0; k < 2; ++k) \
;       acc[ai][bj][m][n] = __builtin_amdgcn_mfma_f32_16x16x32_bf16(Bt_[n][k], At[m][k], acc[ai][bj][m][n], 0, 0, 0); \
;     __builtin_amdgcn_s_setprio(0); } while (0)
; #define WAIT_V(n) asm volatile("s_waitcnt vmcnt(" #n ")" ::: "memory")
; #define WAIT_L(n) asm volatile("s_waitcnt lgkmcnt(" #n ")" ::: "memory")
; #define BAR __builtin_amdgcn_s_barrier()
; #define SCHED __builtin_amdgcn_sched_barrier(0)
; template <int MODE>
; DEV void gemm_phase(const bf16_t* __restrict__ A, const bf16_t* __restrict__ Bt, int M, int N, int K, bf16_t* __restrict__ Out, int ldo,
;                     const float* __restrict__ rstd, const float* __restrict__ rope) {
;     ...
;     for (int t = 0; t < nt; t += 2) {
;       const bool last = (t == nt - 2);
;       const char* a1 = cA + (size_t)(t + 1) * 128;
;       const char* a2 = last ? nA : cA + (size_t)(t + 2) * 128; const char* b2 = last ? nB : cB + (size_t)(t + 2) * 128;
;       const char* a3 = a2 + 128; const char* b3 = b2 + 128;
;       LDB(B0, 0, 0); LDB(B1, 0, 1); SCHED; LDA(At, 0, 0); STAGE_A(SA(1, 1), a1 + hstep);
;       WAIT_V(8); WAIT_L(0); BAR; MMA(0, 0, At, B0); MMA(0, 1, At, B1); BAR; SCHED;
;       LDA(At, 0, 1); STAGE_B(SB_(0, 0), b2); STAGE_B(SB_(0, 1), b2 + hstep); STAGE_A(SA(0, 0), a2);
.LBB0_493:
	s_add_u32 s20, s18, 0xfff80080
	s_addc_u32 s21, s19, -1
	s_add_i32 s39, 0, 0x10000
	s_cmp_eq_u32 s38, 28
	s_cselect_b32 s23, s15, s21
	s_cselect_b32 s22, s14, s20
	v_add_u32_e32 v143, s39, v141
	s_cselect_b32 s21, s13, s37
	s_cselect_b32 s20, s11, s36
	s_add_i32 s42, 0, 0x14000
	ds_read_b128 v[144:147], v143
	ds_read_b128 v[148:151], v143 offset:1024
	ds_read_b128 v[152:155], v143 offset:2048
	ds_read_b128 v[156:159], v143 offset:3072
	v_add_u32_e32 v143, s42, v141
	ds_read_b128 v[160:163], v143
	ds_read_b128 v[164:167], v143 offset:1024
	ds_read_b128 v[168:171], v143 offset:2048
	ds_read_b128 v[172:175], v143 offset:3072
	v_lshl_add_u64 v[212:213], s[18:19], 0, v[136:137]
	s_add_i32 m0, s25, 0xc000
	ds_read_b128 v[176:179], v142
	ds_read_b128 v[180:183], v142 offset:1024
	ds_read_b128 v[184:187], v142 offset:2048
	ds_read_b128 v[188:191], v142 offset:3072
	ds_read_b128 v[194:197], v142 offset:4096
	ds_read_b128 v[198:201], v142 offset:5120
	ds_read_b128 v[202:205], v142 offset:6144
	ds_read_b128 v[206:209], v142 offset:7168
	global_load_lds_dwordx4 v[212:213], off
	v_lshl_add_u64 v[212:213], s[18:19], 0, v[138:139]
	s_add_i32 m0, s25, 0xe000
	s_nop 0
	global_load_lds_dwordx4 v[212:213], off
	s_waitcnt vmcnt(8)
	s_waitcnt lgkmcnt(0)
	s_barrier
	s_setprio 1
	s_waitcnt lgkmcnt(0)
	v_mfma_f32_16x16x32_bf16 v[124:127], v[144:147], v[176:179], v[124:127]
	v_mfma_f32_16x16x32_bf16 v[120:123], v[152:155], v[176:179], v[120:123]
	v_mfma_f32_16x16x32_bf16 v[116:119], v[144:147], v[184:187], v[116:119]
	v_mfma_f32_16x16x32_bf16 v[112:115], v[152:155], v[184:187], v[112:115]
	v_mfma_f32_16x16x32_bf16 v[100:103], v[144:147], v[194:197], v[100:103]
	v_mfma_f32_16x16x32_bf16 v[96:99], v[152:155], v[194:197], v[96:99]
	v_mfma_f32_16x16x32_bf16 v[84:87], v[144:147], v[202:205], v[84:87]
	v_mfma_f32_16x16x32_bf16 v[80:83], v[152:155], v[202:205], v[80:83]
	v_mfma_f32_16x16x32_bf16 v[124:127], v[148:151], v[180:183], v[124:127]
	v_mfma_f32_16x16x32_bf16 v[120:123], v[156:159], v[180:183], v[120:123]
	v_mfma_f32_16x16x32_bf16 v[116:119], v[148:151], v[188:191], v[116:119]
	v_mfma_f32_16x16x32_bf16 v[112:115], v[156:159], v[188:191], v[112:115]
	v_mfma_f32_16x16x32_bf16 v[100:103], v[148:151], v[198:201], v[100:103]
	v_mfma_f32_16x16x32_bf16 v[96:99], v[156:159], v[198:201], v[96:99]
	v_mfma_f32_16x16x32_bf16 v[84:87], v[148:151], v[206:209], v[84:87]
	v_mfma_f32_16x16x32_bf16 v[80:83], v[156:159], v[206:209], v[80:83]
	v_mfma_f32_16x16x32_bf16 v[108:111], v[160:163], v[176:179], v[108:111]
	v_mfma_f32_16x16x32_bf16 v[104:107], v[168:171], v[176:179], v[104:107]
	v_mfma_f32_16x16x32_bf16 v[92:95], v[160:163], v[184:187], v[92:95]
	v_mfma_f32_16x16x32_bf16 v[88:91], v[168:171], v[184:187], v[88:91]
	v_mfma_f32_16x16x32_bf16 v[76:79], v[160:163], v[194:197], v[76:79]
	v_mfma_f32_16x16x32_bf16 v[72:75], v[168:171], v[194:197], v[72:75]
	v_mfma_f32_16x16x32_bf16 v[68:71], v[160:163], v[202:205], v[68:71]
	v_mfma_f32_16x16x32_bf16 v[64:67], v[168:171], v[202:205], v[64:67]
	v_mfma_f32_16x16x32_bf16 v[108:111], v[164:167], v[180:183], v[108:111]
	v_mfma_f32_16x16x32_bf16 v[104:107], v[172:175], v[180:183], v[104:107]
	v_mfma_f32_16x16x32_bf16 v[92:95], v[164:167], v[188:191], v[92:95]
	v_mfma_f32_16x16x32_bf16 v[88:91], v[172:175], v[188:191], v[88:91]
	v_mfma_f32_16x16x32_bf16 v[76:79], v[164:167], v[198:201], v[76:79]
	v_mfma_f32_16x16x32_bf16 v[72:75], v[172:175], v[198:201], v[72:75]
	v_mfma_f32_16x16x32_bf16 v[68:71], v[164:167], v[206:209], v[68:71]
	v_mfma_f32_16x16x32_bf16 v[64:67], v[172:175], v[206:209], v[64:67]
	s_setprio 0
	s_barrier
	s_add_i32 s39, s39, s24
	v_lshl_add_u64 v[212:213], s[20:21], 0, v[192:193]
	s_mov_b32 m0, s39
	ds_read_b128 v[176:179], v142 offset:16384
	ds_read_b128 v[180:183], v142 offset:17408
	ds_read_b128 v[184:187], v142 offset:18432
	ds_read_b128 v[188:191], v142 offset:19456
	ds_read_b128 v[194:197], v142 offset:20480
	ds_read_b128 v[198:201], v142 offset:21504
	ds_read_b128 v[202:205], v142 offset:22528
	ds_read_b128 v[206:209], v142 offset:23552
	global_load_lds_dwordx4 v[212:213], off
	s_add_i32 m0, s39, 0x2000
	s_add_u32 s40, s20, 0x80000
	v_lshl_add_u64 v[214:215], s[20:21], 0, v[128:129]
	s_addc_u32 s41, s21, 0
	s_add_i32 s39, s42, s24
	global_load_lds_dwordx4 v[214:215], off
	v_lshl_add_u64 v[222:223], s[40:41], 0, v[192:193]
	s_mov_b32 m0, s39
	v_lshl_add_u64 v[224:225], s[22:23], 0, v[130:131]
	global_load_lds_dwordx4 v[222:223], off
	v_lshl_add_u64 v[222:223], s[40:41], 0, v[128:129]
	s_add_i32 m0, s39, 0x2000
	s_nop 0
	global_load_lds_dwordx4 v[222:223], off
	v_lshl_add_u64 v[222:223], s[22:23], 0, v[132:133]
	s_mov_b32 m0, s25
	s_nop 0
	global_load_lds_dwordx4 v[222:223], off
	s_mov_b32 m0, s26
	s_nop 0
	global_load_lds_dwordx4 v[224:225], off
	s_waitcnt vmcnt(8)
	s_waitcnt lgkmcnt(0)
	s_barrier
; #define STAGE_A(bufoff, gbase) STAGEX(bufoff, gbase, voffA)
; #define LDA(dst, b, h) do { _Pragma("unroll") for (int m = 0; m < 4; ++m) _Pragma("unroll") for (int k = 0; k < 2; ++k) dst[m][k] = *(const __attribute__((address_space(3))) bf16x8*)(lds + SA(b, h) + aoff + m * 2048 + k * 1024); } while (0)
; #define LDB(dst, b, h) do { _Pragma("unroll") for (int n = 0; n < 2; ++n) _Pragma("unroll") for (int k = 0; k < 2; ++k) dst[n][k] = *(const __attribute__((address_space(3))) bf16x8*)(lds + SB_(b, h) + boff + n * 2048 + k * 1024); } while (0)
; #define MMA(ai, bj, At, Bt_) do { __builtin_amdgcn_s_setprio(1); _Pragma("unroll") for (int m = 0; m < 4; ++m) _Pragma("unroll") for (int n = 0; n < 2; ++n) _Pragma("unroll") for (int k = 0; k < 2; ++k) \
;       acc[ai][bj][m][n] = __builtin_amdgcn_mfma_f32_16x16x32_bf16(Bt_[n][k], At[m][k], acc[ai][bj][m][n], 0, 0, 0); \
;     __builtin_amdgcn_s_setprio(0); } while (0)
; #define WAIT_V(n) asm volatile("s_waitcnt vmcnt(" #n ")" ::: "memory")
; #define WAIT_L(n) asm volatile("s_waitcnt lgkmcnt(" #n ")" ::: "memory")
; #define BAR __builtin_amdgcn_s_barrier()
; #define SCHED __builtin_amdgcn_sched_barrier(0)
; template <int MODE>
; DEV void gemm_phase(const bf16_t* __restrict__ A, const bf16_t* __restrict__ Bt, int M, int N, int K, bf16_t* __restrict__ Out, int ldo,
;                     const float* __restrict__ rstd, const float* __restrict__ rope) {
;     ...
;       WAIT_V(8); WAIT_L(0); BAR; MMA(1, 0, At, B0); MMA(1, 1, At, B1); BAR; SCHED;
;       LDB(B0, 1, 0); LDB(B1, 1, 1); SCHED; LDA(At, 1, 0); STAGE_A(SA(0, 1), a2 + hstep);
;       WAIT_V(8); WAIT_L(0); BAR; MMA(0, 0, At, B0); MMA(0, 1, At, B1); BAR; SCHED;
	s_setprio 1
	s_waitcnt lgkmcnt(0)
	v_mfma_f32_16x16x32_bf16 v[60:63], v[144:147], v[176:179], v[60:63]
	v_mfma_f32_16x16x32_bf16 v[56:59], v[152:155], v[176:179], v[56:59]
	v_mfma_f32_16x16x32_bf16 v[52:55], v[144:147], v[184:187], v[52:55]
	v_mfma_f32_16x16x32_bf16 v[48:51], v[152:155], v[184:187], v[48:51]
	v_mfma_f32_16x16x32_bf16 v[36:39], v[144:147], v[194:197], v[36:39]
	v_mfma_f32_16x16x32_bf16 v[32:35], v[152:155], v[194:197], v[32:35]
	v_mfma_f32_16x16x32_bf16 v[20:23], v[144:147], v[202:205], v[20:23]
	v_mfma_f32_16x16x32_bf16 v[16:19], v[152:155], v[202:205], v[16:19]
	v_mfma_f32_16x16x32_bf16 v[60:63], v[148:151], v[180:183], v[60:63]
	v_mfma_f32_16x16x32_bf16 v[56:59], v[156:159], v[180:183], v[56:59]
	v_mfma_f32_16x16x32_bf16 v[52:55], v[148:151], v[188:191], v[52:55]
	v_mfma_f32_16x16x32_bf16 v[48:51], v[156:159], v[188:191], v[48:51]
	v_mfma_f32_16x16x32_bf16 v[36:39], v[148:151], v[198:201], v[36:39]
	v_mfma_f32_16x16x32_bf16 v[32:35], v[156:159], v[198:201], v[32:35]
	v_mfma_f32_16x16x32_bf16 v[20:23], v[148:151], v[206:209], v[20:23]
	v_mfma_f32_16x16x32_bf16 v[16:19], v[156:159], v[206:209], v[16:19]
	v_mfma_f32_16x16x32_bf16 v[44:47], v[160:163], v[176:179], v[44:47]
	v_mfma_f32_16x16x32_bf16 v[40:43], v[168:171], v[176:179], v[40:43]
	v_mfma_f32_16x16x32_bf16 v[28:31], v[160:163], v[184:187], v[28:31]
	v_mfma_f32_16x16x32_bf16 v[24:27], v[168:171], v[184:187], v[24:27]
	v_mfma_f32_16x16x32_bf16 v[12:15], v[160:163], v[194:197], v[12:15]
	v_mfma_f32_16x16x32_bf16 v[8:11], v[168:171], v[194:197], v[8:11]
	v_mfma_f32_16x16x32_bf16 v[4:7], v[160:163], v[202:205], v[4:7]
	v_mfma_f32_16x16x32_bf16 v[0:3], v[168:171], v[202:205], v[0:3]
	v_mfma_f32_16x16x32_bf16 v[44:47], v[164:167], v[180:183], v[44:47]
	v_mfma_f32_16x16x32_bf16 v[40:43], v[172:175], v[180:183], v[40:43]
	v_mfma_f32_16x16x32_bf16 v[28:31], v[164:167], v[188:191], v[28:31]
	v_mfma_f32_16x16x32_bf16 v[24:27], v[172:175], v[188:191], v[24:27]
	v_mfma_f32_16x16x32_bf16 v[12:15], v[164:167], v[198:201], v[12:15]
	v_mfma_f32_16x16x32_bf16 v[8:11], v[172:175], v[198:201], v[8:11]
	v_mfma_f32_16x16x32_bf16 v[4:7], v[164:167], v[206:209], v[4:7]
	v_mfma_f32_16x16x32_bf16 v[0:3], v[172:175], v[206:209], v[0:3]
	s_setprio 0
	s_barrier
	s_add_i32 s39, 0, 0x18000
	v_add_u32_e32 v143, s39, v141
	s_add_i32 s40, 0, 0x1c000
	ds_read_b128 v[144:147], v143
	ds_read_b128 v[148:151], v143 offset:1024
	ds_read_b128 v[152:155], v143 offset:2048
	ds_read_b128 v[156:159], v143 offset:3072
	v_add_u32_e32 v143, s40, v141
	ds_read_b128 v[160:163], v143
	ds_read_b128 v[164:167], v143 offset:1024
	ds_read_b128 v[168:171], v143 offset:2048
	ds_read_b128 v[172:175], v143 offset:3072
	s_add_u32 s22, s22, 0x80000
	s_addc_u32 s23, s23, 0
	s_mov_b32 m0, s27
	v_lshl_add_u64 v[226:227], s[22:23], 0, v[132:133]
	ds_read_b128 v[176:179], v142 offset:32768
	ds_read_b128 v[180:183], v142 offset:33792
	ds_read_b128 v[184:187], v142 offset:34816
	ds_read_b128 v[188:191], v142 offset:35840
	ds_read_b128 v[194:197], v142 offset:36864
	ds_read_b128 v[198:201], v142 offset:37888
	ds_read_b128 v[202:205], v142 offset:38912
	ds_read_b128 v[206:209], v142 offset:39936
	global_load_lds_dwordx4 v[226:227], off
	v_lshl_add_u64 v[226:227], s[22:23], 0, v[130:131]
	s_mov_b32 m0, s28
	s_nop 0
	global_load_lds_dwordx4 v[226:227], off
	s_waitcnt vmcnt(8)
	s_waitcnt lgkmcnt(0)
	s_barrier
	s_setprio 1
	s_waitcnt lgkmcnt(0)
	v_mfma_f32_16x16x32_bf16 v[124:127], v[144:147], v[176:179], v[124:127]
	v_mfma_f32_16x16x32_bf16 v[120:123], v[152:155], v[176:179], v[120:123]
	v_mfma_f32_16x16x32_bf16 v[116:119], v[144:147], v[184:187], v[116:119]
	v_mfma_f32_16x16x32_bf16 v[112:115], v[152:155], v[184:187], v[112:115]
	v_mfma_f32_16x16x32_bf16 v[100:103], v[144:147], v[194:197], v[100:103]
	v_mfma_f32_16x16x32_bf16 v[96:99], v[152:155], v[194:197], v[96:99]
	v_mfma_f32_16x16x32_bf16 v[84:87], v[144:147], v[202:205], v[84:87]
	v_mfma_f32_16x16x32_bf16 v[80:83], v[152:155], v[202:205], v[80:83]
	v_mfma_f32_16x16x32_bf16 v[124:127], v[148:151], v[180:183], v[124:127]
	v_mfma_f32_16x16x32_bf16 v[120:123], v[156:159], v[180:183], v[120:123]
	v_mfma_f32_16x16x32_bf16 v[116:119], v[148:151], v[188:191], v[116:119]
	v_mfma_f32_16x16x32_bf16 v[112:115], v[156:159], v[188:191], v[112:115]
	v_mfma_f32_16x16x32_bf16 v[100:103], v[148:151], v[198:201], v[100:103]
	v_mfma_f32_16x16x32_bf16 v[96:99], v[156:159], v[198:201], v[96:99]
	v_mfma_f32_16x16x32_bf16 v[84:87], v[148:151], v[206:209], v[84:87]
	v_mfma_f32_16x16x32_bf16 v[80:83], v[156:159], v[206:209], v[80:83]
	v_mfma_f32_16x16x32_bf16 v[108:111], v[160:163], v[176:179], v[108:111]
	v_mfma_f32_16x16x32_bf16 v[104:107], v[168:171], v[176:179], v[104:107]
	v_mfma_f32_16x16x32_bf16 v[92:95], v[160:163], v[184:187], v[92:95]
	v_mfma_f32_16x16x32_bf16 v[88:91], v[168:171], v[184:187], v[88:91]
	v_mfma_f32_16x16x32_bf16 v[76:79], v[160:163], v[194:197], v[76:79]
	v_mfma_f32_16x16x32_bf16 v[72:75], v[168:171], v[194:197], v[72:75]
	v_mfma_f32_16x16x32_bf16 v[68:71], v[160:163], v[202:205], v[68:71]
	v_mfma_f32_16x16x32_bf16 v[64:67], v[168:171], v[202:205], v[64:67]
	v_mfma_f32_16x16x32_bf16 v[108:111], v[164:167], v[180:183], v[108:111]
	v_mfma_f32_16x16x32_bf16 v[104:107], v[172:175], v[180:183], v[104:107]
	v_mfma_f32_16x16x32_bf16 v[92:95], v[164:167], v[188:191], v[92:95]
	v_mfma_f32_16x16x32_bf16 v[88:91], v[172:175], v[188:191], v[88:91]
	v_mfma_f32_16x16x32_bf16 v[76:79], v[164:167], v[198:201], v[76:79]
	v_mfma_f32_16x16x32_bf16 v[72:75], v[172:175], v[198:201], v[72:75]
	v_mfma_f32_16x16x32_bf16 v[68:71], v[164:167], v[206:209], v[68:71]
	v_mfma_f32_16x16x32_bf16 v[64:67], v[172:175], v[206:209], v[64:67]
	s_setprio 0
	s_barrier
; #define STAGE_A(bufoff, gbase) STAGEX(bufoff, gbase, voffA)
; #define STAGE_B(bufoff, gbase) STAGEX(bufoff, gbase, voffB)
; #define LDA(dst, b, h) do { _Pragma("unroll") for (int m = 0; m < 4; ++m) _Pragma("unroll") for (int k = 0; k < 2; ++k) dst[m][k] = *(const __attribute__((address_space(3))) bf16x8*)(lds + SA(b, h) + aoff + m * 2048 + k * 1024); } while (0)
; #define MMA(ai, bj, At, Bt_) do { __builtin_amdgcn_s_setprio(1); _Pragma("unroll") for (int m = 0; m < 4; ++m) _Pragma("unroll") for (int n = 0; n < 2; ++n) _Pragma("unroll") for (int k = 0; k < 2; ++k) \
;       acc[ai][bj][m][n] = __builtin_amdgcn_mfma_f32_16x16x32_bf16(Bt_[n][k], At[m][k], acc[ai][bj][m][n], 0, 0, 0); \
;     __builtin_amdgcn_s_setprio(0); } while (0)
; #define WAIT_V(n) asm volatile("s_waitcnt vmcnt(" #n ")" ::: "memory")
; #define WAIT_L(n) asm volatile("s_waitcnt lgkmcnt(" #n ")" ::: "memory")
; #define BAR __builtin_amdgcn_s_barrier()
; #define SCHED __builtin_amdgcn_sched_barrier(0)
; template <int MODE>
; DEV void gemm_phase(const bf16_t* __restrict__ A, const bf16_t* __restrict__ Bt, int M, int N, int K, bf16_t* __restrict__ Out, int ldo,
;                     const float* __restrict__ rstd, const float* __restrict__ rope) {
;     ...
;       LDA(At, 1, 1); STAGE_B(SB_(1, 0), b3); STAGE_B(SB_(1, 1), b3 + hstep); STAGE_A(SA(1, 0), a3);
;       WAIT_V(8); WAIT_L(0); BAR; MMA(1, 0, At, B0); MMA(1, 1, At, B1); BAR; SCHED;
;     }
	s_add_i32 s22, s39, s24
	v_lshl_add_u64 v[212:213], v[212:213], 0, s[44:45]
	s_mov_b32 m0, s22
	ds_read_b128 v[176:179], v142 offset:49152
	ds_read_b128 v[180:183], v142 offset:50176
	ds_read_b128 v[184:187], v142 offset:51200
	ds_read_b128 v[188:191], v142 offset:52224
	ds_read_b128 v[194:197], v142 offset:53248
	ds_read_b128 v[198:201], v142 offset:54272
	ds_read_b128 v[202:205], v142 offset:55296
	ds_read_b128 v[206:209], v142 offset:56320
	global_load_lds_dwordx4 v[212:213], off
	s_add_i32 m0, s22, 0x2000
	s_add_u32 s20, s20, 0x80080
	v_lshl_add_u64 v[212:213], v[214:215], 0, s[44:45]
	s_addc_u32 s21, s21, 0
	s_add_i32 s22, s40, s24
	global_load_lds_dwordx4 v[212:213], off
	v_lshl_add_u64 v[212:213], s[20:21], 0, v[192:193]
	s_mov_b32 m0, s22
	s_nop 0
	global_load_lds_dwordx4 v[212:213], off
	v_lshl_add_u64 v[212:213], s[20:21], 0, v[128:129]
	s_add_i32 m0, s22, 0x2000
	s_nop 0
	global_load_lds_dwordx4 v[212:213], off
	v_lshl_add_u64 v[212:213], v[222:223], 0, s[44:45]
	s_mov_b32 m0, s29
	s_nop 0
	global_load_lds_dwordx4 v[212:213], off
	v_lshl_add_u64 v[212:213], v[224:225], 0, s[44:45]
	s_mov_b32 m0, s30
	s_nop 0
	global_load_lds_dwordx4 v[212:213], off
	s_waitcnt vmcnt(8)
	s_waitcnt lgkmcnt(0)
	s_barrier
	s_setprio 1
	s_waitcnt lgkmcnt(0)
	v_mfma_f32_16x16x32_bf16 v[60:63], v[144:147], v[176:179], v[60:63]
	v_mfma_f32_16x16x32_bf16 v[56:59], v[152:155], v[176:179], v[56:59]
	v_mfma_f32_16x16x32_bf16 v[52:55], v[144:147], v[184:187], v[52:55]
	v_mfma_f32_16x16x32_bf16 v[48:51], v[152:155], v[184:187], v[48:51]
	v_mfma_f32_16x16x32_bf16 v[36:39], v[144:147], v[194:197], v[36:39]
	v_mfma_f32_16x16x32_bf16 v[32:35], v[152:155], v[194:197], v[32:35]
	v_mfma_f32_16x16x32_bf16 v[20:23], v[144:147], v[202:205], v[20:23]
	v_mfma_f32_16x16x32_bf16 v[16:19], v[152:155], v[202:205], v[16:19]
	v_mfma_f32_16x16x32_bf16 v[60:63], v[148:151], v[180:183], v[60:63]
	v_mfma_f32_16x16x32_bf16 v[56:59], v[156:159], v[180:183], v[56:59]
	v_mfma_f32_16x16x32_bf16 v[52:55], v[148:151], v[188:191], v[52:55]
	v_mfma_f32_16x16x32_bf16 v[48:51], v[156:159], v[188:191], v[48:51]
	v_mfma_f32_16x16x32_bf16 v[36:39], v[148:151], v[198:201], v[36:39]
	v_mfma_f32_16x16x32_bf16 v[32:35], v[156:159], v[198:201], v[32:35]
	v_mfma_f32_16x16x32_bf16 v[20:23], v[148:151], v[206:209], v[20:23]
	v_mfma_f32_16x16x32_bf16 v[16:19], v[156:159], v[206:209], v[16:19]
	v_mfma_f32_16x16x32_bf16 v[44:47], v[160:163], v[176:179], v[44:47]
	v_mfma_f32_16x16x32_bf16 v[40:43], v[168:171], v[176:179], v[40:43]
	v_mfma_f32_16x16x32_bf16 v[28:31], v[160:163], v[184:187], v[28:31]
	v_mfma_f32_16x16x32_bf16 v[24:27], v[168:171], v[184:187], v[24:27]
	v_mfma_f32_16x16x32_bf16 v[12:15], v[160:163], v[194:197], v[12:15]
	v_mfma_f32_16x16x32_bf16 v[8:11], v[168:171], v[194:197], v[8:11]
	v_mfma_f32_16x16x32_bf16 v[4:7], v[160:163], v[202:205], v[4:7]
	v_mfma_f32_16x16x32_bf16 v[0:3], v[168:171], v[202:205], v[0:3]
	v_mfma_f32_16x16x32_bf16 v[44:47], v[164:167], v[180:183], v[44:47]
	v_mfma_f32_16x16x32_bf16 v[40:43], v[172:175], v[180:183], v[40:43]
	v_mfma_f32_16x16x32_bf16 v[28:31], v[164:167], v[188:191], v[28:31]
	v_mfma_f32_16x16x32_bf16 v[24:27], v[172:175], v[188:191], v[24:27]
	v_mfma_f32_16x16x32_bf16 v[12:15], v[164:167], v[198:201], v[12:15]
	v_mfma_f32_16x16x32_bf16 v[8:11], v[172:175], v[198:201], v[8:11]
	v_mfma_f32_16x16x32_bf16 v[4:7], v[164:167], v[206:209], v[4:7]
	v_mfma_f32_16x16x32_bf16 v[0:3], v[172:175], v[206:209], v[0:3]
	s_setprio 0
	s_barrier
	s_add_i32 s38, s38, 2
	s_add_u32 s18, s18, 0x100
	s_addc_u32 s19, s19, 0
	s_add_u32 s36, s36, 0x100
	s_addc_u32 s37, s37, 0
	s_cmp_gt_u32 s38, 29
	s_cbranch_scc0 .LBB0_493
	s_and_b64 vcc, exec, s[6:7]
	s_cbranch_vccz .LBB0_496
	s_barrier

; #define STAGE_A(bufoff, gbase) STAGEX(bufoff, gbase, voffA)
; #define STAGE_B(bufoff, gbase) STAGEX(bufoff, gbase, voffB)
; #define LDA(dst, b, h) do { _Pragma("unroll") for (int m = 0; m < 4; ++m) _Pragma("unroll") for (int k = 0; k < 2; ++k) dst[m][k] = *(const __attribute__((address_space(3))) bf16x8*)(lds + SA(b, h) + aoff + m * 2048 + k * 1024); } while (0)
; #define LDB(dst, b, h) do { _Pragma("unroll") for (int n = 0; n < 2; ++n) _Pragma("unroll") for (int k = 0; k < 2; ++k) dst[n][k] = *(const __attribute__((address_space(3))) bf16x8*)(lds + SB_(b, h) + boff + n * 2048 + k * 1024); } while (0)
; #define MMA(ai, bj, At, Bt_) do { __builtin_amdgcn_s_setprio(1); _Pragma("unroll") for (int m = 0; m < 4; ++m) _Pragma("unroll") for (int n = 0; n < 2; ++n) _Pragma("unroll") for (int k = 0; k < 2; ++k) \
;       acc[ai][bj][m][n] = __builtin_amdgcn_mfma_f32_16x16x32_bf16(Bt_[n][k], At[m][k], acc[ai][bj][m][n], 0, 0, 0); \
;     __builtin_amdgcn_s_setprio(0); } while (0)
; #define WAIT_V(n) asm volatile("s_waitcnt vmcnt(" #n ")" ::: "memory")
; #define WAIT_L(n) asm volatile("s_waitcnt lgkmcnt(" #n ")" ::: "memory")
; #define BAR __builtin_amdgcn_s_barrier()
; #define SCHED __builtin_amdgcn_sched_barrier(0)
; template <int MODE>
; DEV void gemm_phase(const bf16_t* __restrict__ A, const bf16_t* __restrict__ Bt, int M, int N, int K, bf16_t* __restrict__ Out, int ldo,
;                     const float* __restrict__ rstd, const float* __restrict__ rope) {
;     ...
;     for (int t = 0; t < nt; t += 2) {
;       const bool last = (t == nt - 2);
;       const char* a1 = cA + (size_t)(t + 1) * 128;
;       const char* a2 = last ? nA : cA + (size_t)(t + 2) * 128; const char* b2 = last ? nB : cB + (size_t)(t + 2) * 128;
;       const char* a3 = a2 + 128; const char* b3 = b2 + 128;
;       LDB(B0, 0, 0); LDB(B1, 0, 1); SCHED; LDA(At, 0, 0); STAGE_A(SA(1, 1), a1 + hstep);
;       WAIT_V(8); WAIT_L(0); BAR; MMA(0, 0, At, B0); MMA(0, 1, At, B1); BAR; SCHED;
;       LDA(At, 0, 1); STAGE_B(SB_(0, 0), b2); STAGE_B(SB_(0, 1), b2 + hstep); STAGE_A(SA(0, 0), a2);
.LBB0_618:
	s_add_u32 s20, s38, s18
	s_addc_u32 s21, s39, s19
	s_add_u32 s20, s20, 0x12200100
	s_addc_u32 s21, s21, 0
	s_add_u32 s43, s40, s18
	s_addc_u32 s44, s41, s19
	s_add_i32 s45, 0, 0x10000
	s_cmpk_eq_i32 s18, 0xf00
	s_cselect_b32 s23, s36, s21
	s_cselect_b32 s22, s9, s20
	v_add_u32_e32 v147, s45, v145
	s_cselect_b32 s21, s37, s44
	s_cselect_b32 s20, s11, s43
	s_add_i32 s43, 0, 0x14000
	ds_read_b128 v[148:151], v147
	ds_read_b128 v[152:155], v147 offset:1024
	ds_read_b128 v[156:159], v147 offset:2048
	ds_read_b128 v[160:163], v147 offset:3072
	v_add_u32_e32 v147, s43, v145
	ds_read_b128 v[164:167], v147
	ds_read_b128 v[168:171], v147 offset:1024
	ds_read_b128 v[172:175], v147 offset:2048
	ds_read_b128 v[176:179], v147 offset:3072
	v_lshl_add_u64 v[222:223], v[140:141], 0, s[18:19]
	s_add_i32 m0, s25, 0xc000
	ds_read_b128 v[180:183], v146
	ds_read_b128 v[184:187], v146 offset:1024
	ds_read_b128 v[188:191], v146 offset:2048
	ds_read_b128 v[194:197], v146 offset:3072
	ds_read_b128 v[198:201], v146 offset:4096
	ds_read_b128 v[202:205], v146 offset:5120
	ds_read_b128 v[206:209], v146 offset:6144
	ds_read_b128 v[212:215], v146 offset:7168
	global_load_lds_dwordx4 v[222:223], off
	v_lshl_add_u64 v[222:223], v[142:143], 0, s[18:19]
	s_add_i32 m0, s25, 0xe000
	s_nop 0
	global_load_lds_dwordx4 v[222:223], off
	s_waitcnt vmcnt(8)
	s_waitcnt lgkmcnt(0)
	s_barrier
	s_setprio 1
	s_waitcnt lgkmcnt(0)
	v_mfma_f32_16x16x32_bf16 v[124:127], v[148:151], v[180:183], v[124:127]
	v_mfma_f32_16x16x32_bf16 v[120:123], v[156:159], v[180:183], v[120:123]
	v_mfma_f32_16x16x32_bf16 v[108:111], v[148:151], v[188:191], v[108:111]
	v_mfma_f32_16x16x32_bf16 v[104:107], v[156:159], v[188:191], v[104:107]
	v_mfma_f32_16x16x32_bf16 v[92:95], v[148:151], v[198:201], v[92:95]
	v_mfma_f32_16x16x32_bf16 v[88:91], v[156:159], v[198:201], v[88:91]
	v_mfma_f32_16x16x32_bf16 v[76:79], v[148:151], v[206:209], v[76:79]
	v_mfma_f32_16x16x32_bf16 v[72:75], v[156:159], v[206:209], v[72:75]
	v_mfma_f32_16x16x32_bf16 v[124:127], v[152:155], v[184:187], v[124:127]
	v_mfma_f32_16x16x32_bf16 v[120:123], v[160:163], v[184:187], v[120:123]
	v_mfma_f32_16x16x32_bf16 v[108:111], v[152:155], v[194:197], v[108:111]
	v_mfma_f32_16x16x32_bf16 v[104:107], v[160:163], v[194:197], v[104:107]
	v_mfma_f32_16x16x32_bf16 v[92:95], v[152:155], v[202:205], v[92:95]
	v_mfma_f32_16x16x32_bf16 v[88:91], v[160:163], v[202:205], v[88:91]
	v_mfma_f32_16x16x32_bf16 v[76:79], v[152:155], v[212:215], v[76:79]
	v_mfma_f32_16x16x32_bf16 v[72:75], v[160:163], v[212:215], v[72:75]
	v_mfma_f32_16x16x32_bf16 v[116:119], v[164:167], v[180:183], v[116:119]
	v_mfma_f32_16x16x32_bf16 v[112:115], v[172:175], v[180:183], v[112:115]
	v_mfma_f32_16x16x32_bf16 v[100:103], v[164:167], v[188:191], v[100:103]
	v_mfma_f32_16x16x32_bf16 v[96:99], v[172:175], v[188:191], v[96:99]
	v_mfma_f32_16x16x32_bf16 v[84:87], v[164:167], v[198:201], v[84:87]
	v_mfma_f32_16x16x32_bf16 v[80:83], v[172:175], v[198:201], v[80:83]
	v_mfma_f32_16x16x32_bf16 v[68:71], v[164:167], v[206:209], v[68:71]
	v_mfma_f32_16x16x32_bf16 v[64:67], v[172:175], v[206:209], v[64:67]
	v_mfma_f32_16x16x32_bf16 v[116:119], v[168:171], v[184:187], v[116:119]
	v_mfma_f32_16x16x32_bf16 v[112:115], v[176:179], v[184:187], v[112:115]
	v_mfma_f32_16x16x32_bf16 v[100:103], v[168:171], v[194:197], v[100:103]
	v_mfma_f32_16x16x32_bf16 v[96:99], v[176:179], v[194:197], v[96:99]
	v_mfma_f32_16x16x32_bf16 v[84:87], v[168:171], v[202:205], v[84:87]
	v_mfma_f32_16x16x32_bf16 v[80:83], v[176:179], v[202:205], v[80:83]
	v_mfma_f32_16x16x32_bf16 v[68:71], v[168:171], v[212:215], v[68:71]
	v_mfma_f32_16x16x32_bf16 v[64:67], v[176:179], v[212:215], v[64:67]
	s_setprio 0
	s_barrier
	s_add_i32 s44, s45, s24
	v_lshl_add_u64 v[222:223], s[20:21], 0, v[192:193]
	s_mov_b32 m0, s44
	ds_read_b128 v[180:183], v146 offset:16384
	ds_read_b128 v[184:187], v146 offset:17408
	ds_read_b128 v[188:191], v146 offset:18432
	ds_read_b128 v[194:197], v146 offset:19456
	ds_read_b128 v[198:201], v146 offset:20480
	ds_read_b128 v[202:205], v146 offset:21504
	ds_read_b128 v[206:209], v146 offset:22528
	ds_read_b128 v[212:215], v146 offset:23552
	global_load_lds_dwordx4 v[222:223], off
	s_add_i32 m0, s44, 0x2000
	s_add_u32 s44, s20, 0x80000
	v_lshl_add_u64 v[224:225], s[20:21], 0, v[128:129]
	s_addc_u32 s45, s21, 0
	s_add_i32 s43, s43, s24
	global_load_lds_dwordx4 v[224:225], off
	v_lshl_add_u64 v[226:227], s[44:45], 0, v[192:193]
	s_mov_b32 m0, s43
	v_lshl_add_u64 v[228:229], s[22:23], 0, v[130:131]
	global_load_lds_dwordx4 v[226:227], off
	v_lshl_add_u64 v[226:227], s[44:45], 0, v[128:129]
	s_add_i32 m0, s43, 0x2000
	s_nop 0
	global_load_lds_dwordx4 v[226:227], off
	v_lshl_add_u64 v[226:227], s[22:23], 0, v[132:133]
	s_mov_b32 m0, s25
	s_nop 0
	global_load_lds_dwordx4 v[226:227], off
	s_mov_b32 m0, s26
	s_nop 0
	global_load_lds_dwordx4 v[228:229], off
	s_waitcnt vmcnt(8)
	s_waitcnt lgkmcnt(0)
	s_barrier
; #define STAGE_A(bufoff, gbase) STAGEX(bufoff, gbase, voffA)
; #define LDA(dst, b, h) do { _Pragma("unroll") for (int m = 0; m < 4; ++m) _Pragma("unroll") for (int k = 0; k < 2; ++k) dst[m][k] = *(const __attribute__((address_space(3))) bf16x8*)(lds + SA(b, h) + aoff + m * 2048 + k * 1024); } while (0)
; #define LDB(dst, b, h) do { _Pragma("unroll") for (int n = 0; n < 2; ++n) _Pragma("unroll") for (int k = 0; k < 2; ++k) dst[n][k] = *(const __attribute__((address_space(3))) bf16x8*)(lds + SB_(b, h) + boff + n * 2048 + k * 1024); } while (0)
; #define MMA(ai, bj, At, Bt_) do { __builtin_amdgcn_s_setprio(1); _Pragma("unroll") for (int m = 0; m < 4; ++m) _Pragma("unroll") for (int n = 0; n < 2; ++n) _Pragma("unroll") for (int k = 0; k < 2; ++k) \
;       acc[ai][bj][m][n] = __builtin_amdgcn_mfma_f32_16x16x32_bf16(Bt_[n][k], At[m][k], acc[ai][bj][m][n], 0, 0, 0); \
;     __builtin_amdgcn_s_setprio(0); } while (0)
; #define WAIT_V(n) asm volatile("s_waitcnt vmcnt(" #n ")" ::: "memory")
; #define WAIT_L(n) asm volatile("s_waitcnt lgkmcnt(" #n ")" ::: "memory")
; #define BAR __builtin_amdgcn_s_barrier()
; #define SCHED __builtin_amdgcn_sched_barrier(0)
; template <int MODE>
; DEV void gemm_phase(const bf16_t* __restrict__ A, const bf16_t* __restrict__ Bt, int M, int N, int K, bf16_t* __restrict__ Out, int ldo,
;                     const float* __restrict__ rstd, const float* __restrict__ rope) {
;     ...
;       WAIT_V(8); WAIT_L(0); BAR; MMA(1, 0, At, B0); MMA(1, 1, At, B1); BAR; SCHED;
;       LDB(B0, 1, 0); LDB(B1, 1, 1); SCHED; LDA(At, 1, 0); STAGE_A(SA(0, 1), a2 + hstep);
;       WAIT_V(8); WAIT_L(0); BAR; MMA(0, 0, At, B0); MMA(0, 1, At, B1); BAR; SCHED;
	s_setprio 1
	s_waitcnt lgkmcnt(0)
	v_mfma_f32_16x16x32_bf16 v[60:63], v[148:151], v[180:183], v[60:63]
	v_mfma_f32_16x16x32_bf16 v[56:59], v[156:159], v[180:183], v[56:59]
	v_mfma_f32_16x16x32_bf16 v[44:47], v[148:151], v[188:191], v[44:47]
	v_mfma_f32_16x16x32_bf16 v[40:43], v[156:159], v[188:191], v[40:43]
	v_mfma_f32_16x16x32_bf16 v[28:31], v[148:151], v[198:201], v[28:31]
	v_mfma_f32_16x16x32_bf16 v[24:27], v[156:159], v[198:201], v[24:27]
	v_mfma_f32_16x16x32_bf16 v[12:15], v[148:151], v[206:209], v[12:15]
	v_mfma_f32_16x16x32_bf16 v[4:7], v[156:159], v[206:209], v[4:7]
	v_mfma_f32_16x16x32_bf16 v[60:63], v[152:155], v[184:187], v[60:63]
	v_mfma_f32_16x16x32_bf16 v[56:59], v[160:163], v[184:187], v[56:59]
	v_mfma_f32_16x16x32_bf16 v[44:47], v[152:155], v[194:197], v[44:47]
	v_mfma_f32_16x16x32_bf16 v[40:43], v[160:163], v[194:197], v[40:43]
	v_mfma_f32_16x16x32_bf16 v[28:31], v[152:155], v[202:205], v[28:31]
	v_mfma_f32_16x16x32_bf16 v[24:27], v[160:163], v[202:205], v[24:27]
	v_mfma_f32_16x16x32_bf16 v[12:15], v[152:155], v[212:215], v[12:15]
	v_mfma_f32_16x16x32_bf16 v[4:7], v[160:163], v[212:215], v[4:7]
	v_mfma_f32_16x16x32_bf16 v[52:55], v[164:167], v[180:183], v[52:55]
	v_mfma_f32_16x16x32_bf16 v[48:51], v[172:175], v[180:183], v[48:51]
	v_mfma_f32_16x16x32_bf16 v[36:39], v[164:167], v[188:191], v[36:39]
	v_mfma_f32_16x16x32_bf16 v[32:35], v[172:175], v[188:191], v[32:35]
	v_mfma_f32_16x16x32_bf16 v[20:23], v[164:167], v[198:201], v[20:23]
	v_mfma_f32_16x16x32_bf16 v[16:19], v[172:175], v[198:201], v[16:19]
	v_mfma_f32_16x16x32_bf16 v[8:11], v[164:167], v[206:209], v[8:11]
	v_mfma_f32_16x16x32_bf16 v[0:3], v[172:175], v[206:209], v[0:3]
	v_mfma_f32_16x16x32_bf16 v[52:55], v[168:171], v[184:187], v[52:55]
	v_mfma_f32_16x16x32_bf16 v[48:51], v[176:179], v[184:187], v[48:51]
	v_mfma_f32_16x16x32_bf16 v[36:39], v[168:171], v[194:197], v[36:39]
	v_mfma_f32_16x16x32_bf16 v[32:35], v[176:179], v[194:197], v[32:35]
	v_mfma_f32_16x16x32_bf16 v[20:23], v[168:171], v[202:205], v[20:23]
	v_mfma_f32_16x16x32_bf16 v[16:19], v[176:179], v[202:205], v[16:19]
	v_mfma_f32_16x16x32_bf16 v[8:11], v[168:171], v[212:215], v[8:11]
	v_mfma_f32_16x16x32_bf16 v[0:3], v[176:179], v[212:215], v[0:3]
	s_setprio 0
	s_barrier
	s_add_i32 s43, 0, 0x18000
	v_add_u32_e32 v147, s43, v145
	s_add_i32 s44, 0, 0x1c000
	ds_read_b128 v[148:151], v147
	ds_read_b128 v[152:155], v147 offset:1024
	ds_read_b128 v[156:159], v147 offset:2048
	ds_read_b128 v[160:163], v147 offset:3072
	v_add_u32_e32 v147, s44, v145
	ds_read_b128 v[164:167], v147
	ds_read_b128 v[168:171], v147 offset:1024
	ds_read_b128 v[172:175], v147 offset:2048
	ds_read_b128 v[176:179], v147 offset:3072
	s_add_u32 s22, s22, 0x80000
	s_addc_u32 s23, s23, 0
	s_mov_b32 m0, s27
	v_lshl_add_u64 v[230:231], s[22:23], 0, v[132:133]
	ds_read_b128 v[180:183], v146 offset:32768
	ds_read_b128 v[184:187], v146 offset:33792
	ds_read_b128 v[188:191], v146 offset:34816
	ds_read_b128 v[194:197], v146 offset:35840
	ds_read_b128 v[198:201], v146 offset:36864
	ds_read_b128 v[202:205], v146 offset:37888
	ds_read_b128 v[206:209], v146 offset:38912
	ds_read_b128 v[212:215], v146 offset:39936
	global_load_lds_dwordx4 v[230:231], off
	v_lshl_add_u64 v[230:231], s[22:23], 0, v[130:131]
	s_mov_b32 m0, s28
	s_nop 0
	global_load_lds_dwordx4 v[230:231], off
	s_waitcnt vmcnt(8)
	s_waitcnt lgkmcnt(0)
	s_barrier
	s_setprio 1
	s_waitcnt lgkmcnt(0)
	v_mfma_f32_16x16x32_bf16 v[124:127], v[148:151], v[180:183], v[124:127]
	v_mfma_f32_16x16x32_bf16 v[120:123], v[156:159], v[180:183], v[120:123]
	v_mfma_f32_16x16x32_bf16 v[108:111], v[148:151], v[188:191], v[108:111]
	v_mfma_f32_16x16x32_bf16 v[104:107], v[156:159], v[188:191], v[104:107]
	v_mfma_f32_16x16x32_bf16 v[92:95], v[148:151], v[198:201], v[92:95]
	v_mfma_f32_16x16x32_bf16 v[88:91], v[156:159], v[198:201], v[88:91]
	v_mfma_f32_16x16x32_bf16 v[76:79], v[148:151], v[206:209], v[76:79]
	v_mfma_f32_16x16x32_bf16 v[72:75], v[156:159], v[206:209], v[72:75]
	v_mfma_f32_16x16x32_bf16 v[124:127], v[152:155], v[184:187], v[124:127]
	v_mfma_f32_16x16x32_bf16 v[120:123], v[160:163], v[184:187], v[120:123]
	v_mfma_f32_16x16x32_bf16 v[108:111], v[152:155], v[194:197], v[108:111]
	v_mfma_f32_16x16x32_bf16 v[104:107], v[160:163], v[194:197], v[104:107]
	v_mfma_f32_16x16x32_bf16 v[92:95], v[152:155], v[202:205], v[92:95]
	v_mfma_f32_16x16x32_bf16 v[88:91], v[160:163], v[202:205], v[88:91]
	v_mfma_f32_16x16x32_bf16 v[76:79], v[152:155], v[212:215], v[76:79]
	v_mfma_f32_16x16x32_bf16 v[72:75], v[160:163], v[212:215], v[72:75]
	v_mfma_f32_16x16x32_bf16 v[116:119], v[164:167], v[180:183], v[116:119]
	v_mfma_f32_16x16x32_bf16 v[112:115], v[172:175], v[180:183], v[112:115]
	v_mfma_f32_16x16x32_bf16 v[100:103], v[164:167], v[188:191], v[100:103]
	v_mfma_f32_16x16x32_bf16 v[96:99], v[172:175], v[188:191], v[96:99]
	v_mfma_f32_16x16x32_bf16 v[84:87], v[164:167], v[198:201], v[84:87]
	v_mfma_f32_16x16x32_bf16 v[80:83], v[172:175], v[198:201], v[80:83]
	v_mfma_f32_16x16x32_bf16 v[68:71], v[164:167], v[206:209], v[68:71]
	v_mfma_f32_16x16x32_bf16 v[64:67], v[172:175], v[206:209], v[64:67]
	v_mfma_f32_16x16x32_bf16 v[116:119], v[168:171], v[184:187], v[116:119]
	v_mfma_f32_16x16x32_bf16 v[112:115], v[176:179], v[184:187], v[112:115]
	v_mfma_f32_16x16x32_bf16 v[100:103], v[168:171], v[194:197], v[100:103]
	v_mfma_f32_16x16x32_bf16 v[96:99], v[176:179], v[194:197], v[96:99]
	v_mfma_f32_16x16x32_bf16 v[84:87], v[168:171], v[202:205], v[84:87]
	v_mfma_f32_16x16x32_bf16 v[80:83], v[176:179], v[202:205], v[80:83]
	v_mfma_f32_16x16x32_bf16 v[68:71], v[168:171], v[212:215], v[68:71]
	v_mfma_f32_16x16x32_bf16 v[64:67], v[176:179], v[212:215], v[64:67]
	s_setprio 0
	s_barrier
; #define STAGE_A(bufoff, gbase) STAGEX(bufoff, gbase, voffA)
; #define STAGE_B(bufoff, gbase) STAGEX(bufoff, gbase, voffB)
; #define LDA(dst, b, h) do { _Pragma("unroll") for (int m = 0; m < 4; ++m) _Pragma("unroll") for (int k = 0; k < 2; ++k) dst[m][k] = *(const __attribute__((address_space(3))) bf16x8*)(lds + SA(b, h) + aoff + m * 2048 + k * 1024); } while (0)
; #define MMA(ai, bj, At, Bt_) do { __builtin_amdgcn_s_setprio(1); _Pragma("unroll") for (int m = 0; m < 4; ++m) _Pragma("unroll") for (int n = 0; n < 2; ++n) _Pragma("unroll") for (int k = 0; k < 2; ++k) \
;       acc[ai][bj][m][n] = __builtin_amdgcn_mfma_f32_16x16x32_bf16(Bt_[n][k], At[m][k], acc[ai][bj][m][n], 0, 0, 0); \
;     __builtin_amdgcn_s_setprio(0); } while (0)
; #define WAIT_V(n) asm volatile("s_waitcnt vmcnt(" #n ")" ::: "memory")
; #define WAIT_L(n) asm volatile("s_waitcnt lgkmcnt(" #n ")" ::: "memory")
; #define BAR __builtin_amdgcn_s_barrier()
; #define SCHED __builtin_amdgcn_sched_barrier(0)
; template <int MODE>
; DEV void gemm_phase(const bf16_t* __restrict__ A, const bf16_t* __restrict__ Bt, int M, int N, int K, bf16_t* __restrict__ Out, int ldo,
;                     const float* __restrict__ rstd, const float* __restrict__ rope) {
;     ...
;       LDA(At, 1, 1); STAGE_B(SB_(1, 0), b3); STAGE_B(SB_(1, 1), b3 + hstep); STAGE_A(SA(1, 0), a3);
;       WAIT_V(8); WAIT_L(0); BAR; MMA(1, 0, At, B0); MMA(1, 1, At, B1); BAR; SCHED;
;     }
	s_add_i32 s22, s43, s24
	v_lshl_add_u64 v[222:223], v[222:223], 0, s[46:47]
	s_mov_b32 m0, s22
	ds_read_b128 v[180:183], v146 offset:49152
	ds_read_b128 v[184:187], v146 offset:50176
	ds_read_b128 v[188:191], v146 offset:51200
	ds_read_b128 v[194:197], v146 offset:52224
	ds_read_b128 v[198:201], v146 offset:53248
	ds_read_b128 v[202:205], v146 offset:54272
	ds_read_b128 v[206:209], v146 offset:55296
	ds_read_b128 v[212:215], v146 offset:56320
	global_load_lds_dwordx4 v[222:223], off
	s_add_i32 m0, s22, 0x2000
	s_add_u32 s20, s20, 0x80080
	v_lshl_add_u64 v[222:223], v[224:225], 0, s[46:47]
	s_addc_u32 s21, s21, 0
	s_add_i32 s22, s44, s24
	global_load_lds_dwordx4 v[222:223], off
	v_lshl_add_u64 v[222:223], s[20:21], 0, v[192:193]
	s_mov_b32 m0, s22
	s_nop 0
	global_load_lds_dwordx4 v[222:223], off
	v_lshl_add_u64 v[222:223], s[20:21], 0, v[128:129]
	s_add_i32 m0, s22, 0x2000
	s_nop 0
	global_load_lds_dwordx4 v[222:223], off
	v_lshl_add_u64 v[222:223], v[226:227], 0, s[46:47]
	s_mov_b32 m0, s29
	s_nop 0
	global_load_lds_dwordx4 v[222:223], off
	v_lshl_add_u64 v[222:223], v[228:229], 0, s[46:47]
	s_mov_b32 m0, s30
	s_nop 0
	global_load_lds_dwordx4 v[222:223], off
	s_waitcnt vmcnt(8)
	s_waitcnt lgkmcnt(0)
	s_barrier
	s_setprio 1
	s_waitcnt lgkmcnt(0)
	v_mfma_f32_16x16x32_bf16 v[60:63], v[148:151], v[180:183], v[60:63]
	v_mfma_f32_16x16x32_bf16 v[56:59], v[156:159], v[180:183], v[56:59]
	v_mfma_f32_16x16x32_bf16 v[44:47], v[148:151], v[188:191], v[44:47]
	v_mfma_f32_16x16x32_bf16 v[40:43], v[156:159], v[188:191], v[40:43]
	v_mfma_f32_16x16x32_bf16 v[28:31], v[148:151], v[198:201], v[28:31]
	v_mfma_f32_16x16x32_bf16 v[24:27], v[156:159], v[198:201], v[24:27]
	v_mfma_f32_16x16x32_bf16 v[12:15], v[148:151], v[206:209], v[12:15]
	v_mfma_f32_16x16x32_bf16 v[4:7], v[156:159], v[206:209], v[4:7]
	v_mfma_f32_16x16x32_bf16 v[60:63], v[152:155], v[184:187], v[60:63]
	v_mfma_f32_16x16x32_bf16 v[56:59], v[160:163], v[184:187], v[56:59]
	v_mfma_f32_16x16x32_bf16 v[44:47], v[152:155], v[194:197], v[44:47]
	v_mfma_f32_16x16x32_bf16 v[40:43], v[160:163], v[194:197], v[40:43]
	v_mfma_f32_16x16x32_bf16 v[28:31], v[152:155], v[202:205], v[28:31]
	v_mfma_f32_16x16x32_bf16 v[24:27], v[160:163], v[202:205], v[24:27]
	v_mfma_f32_16x16x32_bf16 v[12:15], v[152:155], v[212:215], v[12:15]
	v_mfma_f32_16x16x32_bf16 v[4:7], v[160:163], v[212:215], v[4:7]
	v_mfma_f32_16x16x32_bf16 v[52:55], v[164:167], v[180:183], v[52:55]
	v_mfma_f32_16x16x32_bf16 v[48:51], v[172:175], v[180:183], v[48:51]
	v_mfma_f32_16x16x32_bf16 v[36:39], v[164:167], v[188:191], v[36:39]
	v_mfma_f32_16x16x32_bf16 v[32:35], v[172:175], v[188:191], v[32:35]
	v_mfma_f32_16x16x32_bf16 v[20:23], v[164:167], v[198:201], v[20:23]
	v_mfma_f32_16x16x32_bf16 v[16:19], v[172:175], v[198:201], v[16:19]
	v_mfma_f32_16x16x32_bf16 v[8:11], v[164:167], v[206:209], v[8:11]
	v_mfma_f32_16x16x32_bf16 v[0:3], v[172:175], v[206:209], v[0:3]
	v_mfma_f32_16x16x32_bf16 v[52:55], v[168:171], v[184:187], v[52:55]
	v_mfma_f32_16x16x32_bf16 v[48:51], v[176:179], v[184:187], v[48:51]
	v_mfma_f32_16x16x32_bf16 v[36:39], v[168:171], v[194:197], v[36:39]
	v_mfma_f32_16x16x32_bf16 v[32:35], v[176:179], v[194:197], v[32:35]
	v_mfma_f32_16x16x32_bf16 v[20:23], v[168:171], v[202:205], v[20:23]
	v_mfma_f32_16x16x32_bf16 v[16:19], v[176:179], v[202:205], v[16:19]
	v_mfma_f32_16x16x32_bf16 v[8:11], v[168:171], v[212:215], v[8:11]
	v_mfma_f32_16x16x32_bf16 v[0:3], v[176:179], v[212:215], v[0:3]
	s_setprio 0
	s_barrier
	s_add_i32 s42, s42, 2
	s_add_u32 s18, s18, 0x100
	s_addc_u32 s19, s19, 0
	s_cmp_gt_u32 s42, 29
	s_cbranch_scc0 .LBB0_618
	s_and_b64 vcc, exec, s[6:7]
	s_cbranch_vccz .LBB0_621
	s_barrier

; #define STAGE_A(bufoff, gbase) STAGEX(bufoff, gbase, voffA)
; #define STAGE_B(bufoff, gbase) STAGEX(bufoff, gbase, voffB)
; #define LDA(dst, b, h) do { _Pragma("unroll") for (int m = 0; m < 4; ++m) _Pragma("unroll") for (int k = 0; k < 2; ++k) dst[m][k] = *(const __attribute__((address_space(3))) bf16x8*)(lds + SA(b, h) + aoff + m * 2048 + k * 1024); } while (0)
; #define LDB(dst, b, h) do { _Pragma("unroll") for (int n = 0; n < 2; ++n) _Pragma("unroll") for (int k = 0; k < 2; ++k) dst[n][k] = *(const __attribute__((address_space(3))) bf16x8*)(lds + SB_(b, h) + boff + n * 2048 + k * 1024); } while (0)
; #define MMA(ai, bj, At, Bt_) do { __builtin_amdgcn_s_setprio(1); _Pragma("unroll") for (int m = 0; m < 4; ++m) _Pragma("unroll") for (int n = 0; n < 2; ++n) _Pragma("unroll") for (int k = 0; k < 2; ++k) \
;       acc[ai][bj][m][n] = __builtin_amdgcn_mfma_f32_16x16x32_bf16(Bt_[n][k], At[m][k], acc[ai][bj][m][n], 0, 0, 0); \
;     __builtin_amdgcn_s_setprio(0); } while (0)
; #define WAIT_V(n) asm volatile("s_waitcnt vmcnt(" #n ")" ::: "memory")
; #define WAIT_L(n) asm volatile("s_waitcnt lgkmcnt(" #n ")" ::: "memory")
; #define BAR __builtin_amdgcn_s_barrier()
; #define SCHED __builtin_amdgcn_sched_barrier(0)
; template <int MODE>
; DEV void gemm_phase(const bf16_t* __restrict__ A, const bf16_t* __restrict__ Bt, int M, int N, int K, bf16_t* __restrict__ Out, int ldo,
;                     const float* __restrict__ rstd, const float* __restrict__ rope) {
;     ...
;     for (int t = 0; t < nt; t += 2) {
;       const bool last = (t == nt - 2);
;       const char* a1 = cA + (size_t)(t + 1) * 128;
;       const char* a2 = last ? nA : cA + (size_t)(t + 2) * 128; const char* b2 = last ? nB : cB + (size_t)(t + 2) * 128;
;       const char* a3 = a2 + 128; const char* b3 = b2 + 128;
;       LDB(B0, 0, 0); LDB(B1, 0, 1); SCHED; LDA(At, 0, 0); STAGE_A(SA(1, 1), a1 + hstep);
;       WAIT_V(8); WAIT_L(0); BAR; MMA(0, 0, At, B0); MMA(0, 1, At, B1); BAR; SCHED;
;       LDA(At, 0, 1); STAGE_B(SB_(0, 0), b2); STAGE_B(SB_(0, 1), b2 + hstep); STAGE_A(SA(0, 0), a2);
.LBB0_690:
	s_add_u32 s14, s12, 0x100
	s_addc_u32 s15, s13, 0
	s_add_i32 s39, 0, 0x10000
	s_cmpk_eq_i32 s38, 0x54
	s_cselect_b32 s19, s9, s15
	s_cselect_b32 s18, s8, s14
	v_add_u32_e32 v143, s39, v141
	s_cselect_b32 s17, s35, s37
	s_cselect_b32 s16, s34, s36
	s_add_i32 s40, 0, 0x14000
	ds_read_b128 v[144:147], v143
	ds_read_b128 v[148:151], v143 offset:1024
	ds_read_b128 v[152:155], v143 offset:2048
	ds_read_b128 v[156:159], v143 offset:3072
	v_add_u32_e32 v143, s40, v141
	ds_read_b128 v[160:163], v143
	ds_read_b128 v[164:167], v143 offset:1024
	ds_read_b128 v[168:171], v143 offset:2048
	ds_read_b128 v[172:175], v143 offset:3072
	v_lshl_add_u64 v[212:213], s[12:13], 0, v[136:137]
	s_add_i32 m0, s21, 0xc000
	ds_read_b128 v[176:179], v142
	ds_read_b128 v[180:183], v142 offset:1024
	ds_read_b128 v[184:187], v142 offset:2048
	ds_read_b128 v[188:191], v142 offset:3072
	ds_read_b128 v[194:197], v142 offset:4096
	ds_read_b128 v[198:201], v142 offset:5120
	ds_read_b128 v[202:205], v142 offset:6144
	ds_read_b128 v[206:209], v142 offset:7168
	global_load_lds_dwordx4 v[212:213], off
	v_lshl_add_u64 v[212:213], s[12:13], 0, v[138:139]
	s_add_i32 m0, s21, 0xe000
	s_nop 0
	global_load_lds_dwordx4 v[212:213], off
	s_waitcnt vmcnt(8)
	s_waitcnt lgkmcnt(0)
	s_barrier
	s_setprio 1
	s_waitcnt lgkmcnt(0)
	v_mfma_f32_16x16x32_bf16 v[124:127], v[144:147], v[176:179], v[124:127]
	v_mfma_f32_16x16x32_bf16 v[120:123], v[152:155], v[176:179], v[120:123]
	v_mfma_f32_16x16x32_bf16 v[116:119], v[144:147], v[184:187], v[116:119]
	v_mfma_f32_16x16x32_bf16 v[112:115], v[152:155], v[184:187], v[112:115]
	v_mfma_f32_16x16x32_bf16 v[100:103], v[144:147], v[194:197], v[100:103]
	v_mfma_f32_16x16x32_bf16 v[96:99], v[152:155], v[194:197], v[96:99]
	v_mfma_f32_16x16x32_bf16 v[84:87], v[144:147], v[202:205], v[84:87]
	v_mfma_f32_16x16x32_bf16 v[80:83], v[152:155], v[202:205], v[80:83]
	v_mfma_f32_16x16x32_bf16 v[124:127], v[148:151], v[180:183], v[124:127]
	v_mfma_f32_16x16x32_bf16 v[120:123], v[156:159], v[180:183], v[120:123]
	v_mfma_f32_16x16x32_bf16 v[116:119], v[148:151], v[188:191], v[116:119]
	v_mfma_f32_16x16x32_bf16 v[112:115], v[156:159], v[188:191], v[112:115]
	v_mfma_f32_16x16x32_bf16 v[100:103], v[148:151], v[198:201], v[100:103]
	v_mfma_f32_16x16x32_bf16 v[96:99], v[156:159], v[198:201], v[96:99]
	v_mfma_f32_16x16x32_bf16 v[84:87], v[148:151], v[206:209], v[84:87]
	v_mfma_f32_16x16x32_bf16 v[80:83], v[156:159], v[206:209], v[80:83]
	v_mfma_f32_16x16x32_bf16 v[108:111], v[160:163], v[176:179], v[108:111]
	v_mfma_f32_16x16x32_bf16 v[104:107], v[168:171], v[176:179], v[104:107]
	v_mfma_f32_16x16x32_bf16 v[92:95], v[160:163], v[184:187], v[92:95]
	v_mfma_f32_16x16x32_bf16 v[88:91], v[168:171], v[184:187], v[88:91]
	v_mfma_f32_16x16x32_bf16 v[76:79], v[160:163], v[194:197], v[76:79]
	v_mfma_f32_16x16x32_bf16 v[72:75], v[168:171], v[194:197], v[72:75]
	v_mfma_f32_16x16x32_bf16 v[68:71], v[160:163], v[202:205], v[68:71]
	v_mfma_f32_16x16x32_bf16 v[64:67], v[168:171], v[202:205], v[64:67]
	v_mfma_f32_16x16x32_bf16 v[108:111], v[164:167], v[180:183], v[108:111]
	v_mfma_f32_16x16x32_bf16 v[104:107], v[172:175], v[180:183], v[104:107]
	v_mfma_f32_16x16x32_bf16 v[92:95], v[164:167], v[188:191], v[92:95]
	v_mfma_f32_16x16x32_bf16 v[88:91], v[172:175], v[188:191], v[88:91]
	v_mfma_f32_16x16x32_bf16 v[76:79], v[164:167], v[198:201], v[76:79]
	v_mfma_f32_16x16x32_bf16 v[72:75], v[172:175], v[198:201], v[72:75]
	v_mfma_f32_16x16x32_bf16 v[68:71], v[164:167], v[206:209], v[68:71]
	v_mfma_f32_16x16x32_bf16 v[64:67], v[172:175], v[206:209], v[64:67]
	s_setprio 0
	s_barrier
	s_add_i32 s12, s39, s20
	v_lshl_add_u64 v[212:213], s[16:17], 0, v[192:193]
	s_mov_b32 m0, s12
	ds_read_b128 v[176:179], v142 offset:16384
	ds_read_b128 v[180:183], v142 offset:17408
	ds_read_b128 v[184:187], v142 offset:18432
	ds_read_b128 v[188:191], v142 offset:19456
	ds_read_b128 v[194:197], v142 offset:20480
	ds_read_b128 v[198:201], v142 offset:21504
	ds_read_b128 v[202:205], v142 offset:22528
	ds_read_b128 v[206:209], v142 offset:23552
	global_load_lds_dwordx4 v[212:213], off
	s_add_i32 m0, s12, 0x2000
	s_add_u32 s12, s16, 0x160000
	v_lshl_add_u64 v[214:215], s[16:17], 0, v[128:129]
	s_addc_u32 s13, s17, 0
	s_add_i32 s39, s40, s20
	global_load_lds_dwordx4 v[214:215], off
	v_lshl_add_u64 v[222:223], s[12:13], 0, v[192:193]
	s_mov_b32 m0, s39
	v_lshl_add_u64 v[224:225], s[18:19], 0, v[130:131]
	global_load_lds_dwordx4 v[222:223], off
	v_lshl_add_u64 v[222:223], s[12:13], 0, v[128:129]
	s_add_i32 m0, s39, 0x2000
	s_nop 0
	global_load_lds_dwordx4 v[222:223], off
	v_lshl_add_u64 v[222:223], s[18:19], 0, v[132:133]
	s_mov_b32 m0, s21
	s_nop 0
	global_load_lds_dwordx4 v[222:223], off
	s_mov_b32 m0, s22
	s_nop 0
	global_load_lds_dwordx4 v[224:225], off
	s_waitcnt vmcnt(8)
	s_waitcnt lgkmcnt(0)
	s_barrier
; #define STAGE_A(bufoff, gbase) STAGEX(bufoff, gbase, voffA)
; #define LDA(dst, b, h) do { _Pragma("unroll") for (int m = 0; m < 4; ++m) _Pragma("unroll") for (int k = 0; k < 2; ++k) dst[m][k] = *(const __attribute__((address_space(3))) bf16x8*)(lds + SA(b, h) + aoff + m * 2048 + k * 1024); } while (0)
; #define LDB(dst, b, h) do { _Pragma("unroll") for (int n = 0; n < 2; ++n) _Pragma("unroll") for (int k = 0; k < 2; ++k) dst[n][k] = *(const __attribute__((address_space(3))) bf16x8*)(lds + SB_(b, h) + boff + n * 2048 + k * 1024); } while (0)
; #define MMA(ai, bj, At, Bt_) do { __builtin_amdgcn_s_setprio(1); _Pragma("unroll") for (int m = 0; m < 4; ++m) _Pragma("unroll") for (int n = 0; n < 2; ++n) _Pragma("unroll") for (int k = 0; k < 2; ++k) \
;       acc[ai][bj][m][n] = __builtin_amdgcn_mfma_f32_16x16x32_bf16(Bt_[n][k], At[m][k], acc[ai][bj][m][n], 0, 0, 0); \
;     __builtin_amdgcn_s_setprio(0); } while (0)
; #define WAIT_V(n) asm volatile("s_waitcnt vmcnt(" #n ")" ::: "memory")
; #define WAIT_L(n) asm volatile("s_waitcnt lgkmcnt(" #n ")" ::: "memory")
; #define BAR __builtin_amdgcn_s_barrier()
; #define SCHED __builtin_amdgcn_sched_barrier(0)
; template <int MODE>
; DEV void gemm_phase(const bf16_t* __restrict__ A, const bf16_t* __restrict__ Bt, int M, int N, int K, bf16_t* __restrict__ Out, int ldo,
;                     const float* __restrict__ rstd, const float* __restrict__ rope) {
;     ...
;       WAIT_V(8); WAIT_L(0); BAR; MMA(1, 0, At, B0); MMA(1, 1, At, B1); BAR; SCHED;
;       LDB(B0, 1, 0); LDB(B1, 1, 1); SCHED; LDA(At, 1, 0); STAGE_A(SA(0, 1), a2 + hstep);
;       WAIT_V(8); WAIT_L(0); BAR; MMA(0, 0, At, B0); MMA(0, 1, At, B1); BAR; SCHED;
	s_setprio 1
	s_waitcnt lgkmcnt(0)
	v_mfma_f32_16x16x32_bf16 v[60:63], v[144:147], v[176:179], v[60:63]
	v_mfma_f32_16x16x32_bf16 v[56:59], v[152:155], v[176:179], v[56:59]
	v_mfma_f32_16x16x32_bf16 v[52:55], v[144:147], v[184:187], v[52:55]
	v_mfma_f32_16x16x32_bf16 v[48:51], v[152:155], v[184:187], v[48:51]
	v_mfma_f32_16x16x32_bf16 v[36:39], v[144:147], v[194:197], v[36:39]
	v_mfma_f32_16x16x32_bf16 v[32:35], v[152:155], v[194:197], v[32:35]
	v_mfma_f32_16x16x32_bf16 v[20:23], v[144:147], v[202:205], v[20:23]
	v_mfma_f32_16x16x32_bf16 v[16:19], v[152:155], v[202:205], v[16:19]
	v_mfma_f32_16x16x32_bf16 v[60:63], v[148:151], v[180:183], v[60:63]
	v_mfma_f32_16x16x32_bf16 v[56:59], v[156:159], v[180:183], v[56:59]
	v_mfma_f32_16x16x32_bf16 v[52:55], v[148:151], v[188:191], v[52:55]
	v_mfma_f32_16x16x32_bf16 v[48:51], v[156:159], v[188:191], v[48:51]
	v_mfma_f32_16x16x32_bf16 v[36:39], v[148:151], v[198:201], v[36:39]
	v_mfma_f32_16x16x32_bf16 v[32:35], v[156:159], v[198:201], v[32:35]
	v_mfma_f32_16x16x32_bf16 v[20:23], v[148:151], v[206:209], v[20:23]
	v_mfma_f32_16x16x32_bf16 v[16:19], v[156:159], v[206:209], v[16:19]
	v_mfma_f32_16x16x32_bf16 v[44:47], v[160:163], v[176:179], v[44:47]
	v_mfma_f32_16x16x32_bf16 v[40:43], v[168:171], v[176:179], v[40:43]
	v_mfma_f32_16x16x32_bf16 v[28:31], v[160:163], v[184:187], v[28:31]
	v_mfma_f32_16x16x32_bf16 v[24:27], v[168:171], v[184:187], v[24:27]
	v_mfma_f32_16x16x32_bf16 v[12:15], v[160:163], v[194:197], v[12:15]
	v_mfma_f32_16x16x32_bf16 v[8:11], v[168:171], v[194:197], v[8:11]
	v_mfma_f32_16x16x32_bf16 v[4:7], v[160:163], v[202:205], v[4:7]
	v_mfma_f32_16x16x32_bf16 v[0:3], v[168:171], v[202:205], v[0:3]
	v_mfma_f32_16x16x32_bf16 v[44:47], v[164:167], v[180:183], v[44:47]
	v_mfma_f32_16x16x32_bf16 v[40:43], v[172:175], v[180:183], v[40:43]
	v_mfma_f32_16x16x32_bf16 v[28:31], v[164:167], v[188:191], v[28:31]
	v_mfma_f32_16x16x32_bf16 v[24:27], v[172:175], v[188:191], v[24:27]
	v_mfma_f32_16x16x32_bf16 v[12:15], v[164:167], v[198:201], v[12:15]
	v_mfma_f32_16x16x32_bf16 v[8:11], v[172:175], v[198:201], v[8:11]
	v_mfma_f32_16x16x32_bf16 v[4:7], v[164:167], v[206:209], v[4:7]
	v_mfma_f32_16x16x32_bf16 v[0:3], v[172:175], v[206:209], v[0:3]
	s_setprio 0
	s_barrier
	s_add_i32 s39, 0, 0x18000
	v_add_u32_e32 v143, s39, v141
	s_add_i32 s40, 0, 0x1c000
	ds_read_b128 v[144:147], v143
	ds_read_b128 v[148:151], v143 offset:1024
	ds_read_b128 v[152:155], v143 offset:2048
	ds_read_b128 v[156:159], v143 offset:3072
	v_add_u32_e32 v143, s40, v141
	ds_read_b128 v[160:163], v143
	ds_read_b128 v[164:167], v143 offset:1024
	ds_read_b128 v[168:171], v143 offset:2048
	ds_read_b128 v[172:175], v143 offset:3072
	s_add_u32 s12, s18, 0x160000
	s_addc_u32 s13, s19, 0
	s_mov_b32 m0, s23
	v_lshl_add_u64 v[226:227], s[12:13], 0, v[132:133]
	ds_read_b128 v[176:179], v142 offset:32768
	ds_read_b128 v[180:183], v142 offset:33792
	ds_read_b128 v[184:187], v142 offset:34816
	ds_read_b128 v[188:191], v142 offset:35840
	ds_read_b128 v[194:197], v142 offset:36864
	ds_read_b128 v[198:201], v142 offset:37888
	ds_read_b128 v[202:205], v142 offset:38912
	ds_read_b128 v[206:209], v142 offset:39936
	global_load_lds_dwordx4 v[226:227], off
	v_lshl_add_u64 v[226:227], s[12:13], 0, v[130:131]
	s_mov_b32 m0, s24
	s_nop 0
	global_load_lds_dwordx4 v[226:227], off
	s_waitcnt vmcnt(8)
	s_waitcnt lgkmcnt(0)
	s_barrier
	s_setprio 1
	s_waitcnt lgkmcnt(0)
	v_mfma_f32_16x16x32_bf16 v[124:127], v[144:147], v[176:179], v[124:127]
	v_mfma_f32_16x16x32_bf16 v[120:123], v[152:155], v[176:179], v[120:123]
	v_mfma_f32_16x16x32_bf16 v[116:119], v[144:147], v[184:187], v[116:119]
	v_mfma_f32_16x16x32_bf16 v[112:115], v[152:155], v[184:187], v[112:115]
	v_mfma_f32_16x16x32_bf16 v[100:103], v[144:147], v[194:197], v[100:103]
	v_mfma_f32_16x16x32_bf16 v[96:99], v[152:155], v[194:197], v[96:99]
	v_mfma_f32_16x16x32_bf16 v[84:87], v[144:147], v[202:205], v[84:87]
	v_mfma_f32_16x16x32_bf16 v[80:83], v[152:155], v[202:205], v[80:83]
	v_mfma_f32_16x16x32_bf16 v[124:127], v[148:151], v[180:183], v[124:127]
	v_mfma_f32_16x16x32_bf16 v[120:123], v[156:159], v[180:183], v[120:123]
	v_mfma_f32_16x16x32_bf16 v[116:119], v[148:151], v[188:191], v[116:119]
	v_mfma_f32_16x16x32_bf16 v[112:115], v[156:159], v[188:191], v[112:115]
	v_mfma_f32_16x16x32_bf16 v[100:103], v[148:151], v[198:201], v[100:103]
	v_mfma_f32_16x16x32_bf16 v[96:99], v[156:159], v[198:201], v[96:99]
	v_mfma_f32_16x16x32_bf16 v[84:87], v[148:151], v[206:209], v[84:87]
	v_mfma_f32_16x16x32_bf16 v[80:83], v[156:159], v[206:209], v[80:83]
	v_mfma_f32_16x16x32_bf16 v[108:111], v[160:163], v[176:179], v[108:111]
	v_mfma_f32_16x16x32_bf16 v[104:107], v[168:171], v[176:179], v[104:107]
	v_mfma_f32_16x16x32_bf16 v[92:95], v[160:163], v[184:187], v[92:95]
	v_mfma_f32_16x16x32_bf16 v[88:91], v[168:171], v[184:187], v[88:91]
	v_mfma_f32_16x16x32_bf16 v[76:79], v[160:163], v[194:197], v[76:79]
	v_mfma_f32_16x16x32_bf16 v[72:75], v[168:171], v[194:197], v[72:75]
	v_mfma_f32_16x16x32_bf16 v[68:71], v[160:163], v[202:205], v[68:71]
	v_mfma_f32_16x16x32_bf16 v[64:67], v[168:171], v[202:205], v[64:67]
	v_mfma_f32_16x16x32_bf16 v[108:111], v[164:167], v[180:183], v[108:111]
	v_mfma_f32_16x16x32_bf16 v[104:107], v[172:175], v[180:183], v[104:107]
	v_mfma_f32_16x16x32_bf16 v[92:95], v[164:167], v[188:191], v[92:95]
	v_mfma_f32_16x16x32_bf16 v[88:91], v[172:175], v[188:191], v[88:91]
	v_mfma_f32_16x16x32_bf16 v[76:79], v[164:167], v[198:201], v[76:79]
	v_mfma_f32_16x16x32_bf16 v[72:75], v[172:175], v[198:201], v[72:75]
	v_mfma_f32_16x16x32_bf16 v[68:71], v[164:167], v[206:209], v[68:71]
	v_mfma_f32_16x16x32_bf16 v[64:67], v[172:175], v[206:209], v[64:67]
	s_setprio 0
	s_barrier
; #define STAGE_A(bufoff, gbase) STAGEX(bufoff, gbase, voffA)
; #define STAGE_B(bufoff, gbase) STAGEX(bufoff, gbase, voffB)
; #define LDA(dst, b, h) do { _Pragma("unroll") for (int m = 0; m < 4; ++m) _Pragma("unroll") for (int k = 0; k < 2; ++k) dst[m][k] = *(const __attribute__((address_space(3))) bf16x8*)(lds + SA(b, h) + aoff + m * 2048 + k * 1024); } while (0)
; #define MMA(ai, bj, At, Bt_) do { __builtin_amdgcn_s_setprio(1); _Pragma("unroll") for (int m = 0; m < 4; ++m) _Pragma("unroll") for (int n = 0; n < 2; ++n) _Pragma("unroll") for (int k = 0; k < 2; ++k) \
;       acc[ai][bj][m][n] = __builtin_amdgcn_mfma_f32_16x16x32_bf16(Bt_[n][k], At[m][k], acc[ai][bj][m][n], 0, 0, 0); \
;     __builtin_amdgcn_s_setprio(0); } while (0)
; #define WAIT_V(n) asm volatile("s_waitcnt vmcnt(" #n ")" ::: "memory")
; #define WAIT_L(n) asm volatile("s_waitcnt lgkmcnt(" #n ")" ::: "memory")
; #define BAR __builtin_amdgcn_s_barrier()
; #define SCHED __builtin_amdgcn_sched_barrier(0)
; template <int MODE>
; DEV void gemm_phase(const bf16_t* __restrict__ A, const bf16_t* __restrict__ Bt, int M, int N, int K, bf16_t* __restrict__ Out, int ldo,
;                     const float* __restrict__ rstd, const float* __restrict__ rope) {
;     ...
;       LDA(At, 1, 1); STAGE_B(SB_(1, 0), b3); STAGE_B(SB_(1, 1), b3 + hstep); STAGE_A(SA(1, 0), a3);
;       WAIT_V(8); WAIT_L(0); BAR; MMA(1, 0, At, B0); MMA(1, 1, At, B1); BAR; SCHED;
;     }
	s_add_i32 s12, s39, s20
	v_lshl_add_u64 v[212:213], v[212:213], 0, s[42:43]
	s_mov_b32 m0, s12
	ds_read_b128 v[176:179], v142 offset:49152
	ds_read_b128 v[180:183], v142 offset:50176
	ds_read_b128 v[184:187], v142 offset:51200
	ds_read_b128 v[188:191], v142 offset:52224
	ds_read_b128 v[194:197], v142 offset:53248
	ds_read_b128 v[198:201], v142 offset:54272
	ds_read_b128 v[202:205], v142 offset:55296
	ds_read_b128 v[206:209], v142 offset:56320
	global_load_lds_dwordx4 v[212:213], off
	s_add_i32 m0, s12, 0x2000
	s_add_u32 s12, s16, 0x160080
	v_lshl_add_u64 v[212:213], v[214:215], 0, s[42:43]
	s_addc_u32 s13, s17, 0
	s_add_i32 s16, s40, s20
	global_load_lds_dwordx4 v[212:213], off
	v_lshl_add_u64 v[212:213], s[12:13], 0, v[192:193]
	s_mov_b32 m0, s16
	s_nop 0
	global_load_lds_dwordx4 v[212:213], off
	v_lshl_add_u64 v[212:213], s[12:13], 0, v[128:129]
	s_add_i32 m0, s16, 0x2000
	s_nop 0
	global_load_lds_dwordx4 v[212:213], off
	v_lshl_add_u64 v[212:213], v[222:223], 0, s[42:43]
	s_mov_b32 m0, s25
	s_nop 0
	global_load_lds_dwordx4 v[212:213], off
	v_lshl_add_u64 v[212:213], v[224:225], 0, s[42:43]
	s_mov_b32 m0, s26
	s_nop 0
	global_load_lds_dwordx4 v[212:213], off
	s_waitcnt vmcnt(8)
	s_waitcnt lgkmcnt(0)
	s_barrier
	s_setprio 1
	s_waitcnt lgkmcnt(0)
	v_mfma_f32_16x16x32_bf16 v[60:63], v[144:147], v[176:179], v[60:63]
	v_mfma_f32_16x16x32_bf16 v[56:59], v[152:155], v[176:179], v[56:59]
	v_mfma_f32_16x16x32_bf16 v[52:55], v[144:147], v[184:187], v[52:55]
	v_mfma_f32_16x16x32_bf16 v[48:51], v[152:155], v[184:187], v[48:51]
	v_mfma_f32_16x16x32_bf16 v[36:39], v[144:147], v[194:197], v[36:39]
	v_mfma_f32_16x16x32_bf16 v[32:35], v[152:155], v[194:197], v[32:35]
	v_mfma_f32_16x16x32_bf16 v[20:23], v[144:147], v[202:205], v[20:23]
	v_mfma_f32_16x16x32_bf16 v[16:19], v[152:155], v[202:205], v[16:19]
	v_mfma_f32_16x16x32_bf16 v[60:63], v[148:151], v[180:183], v[60:63]
	v_mfma_f32_16x16x32_bf16 v[56:59], v[156:159], v[180:183], v[56:59]
	v_mfma_f32_16x16x32_bf16 v[52:55], v[148:151], v[188:191], v[52:55]
	v_mfma_f32_16x16x32_bf16 v[48:51], v[156:159], v[188:191], v[48:51]
	v_mfma_f32_16x16x32_bf16 v[36:39], v[148:151], v[198:201], v[36:39]
	v_mfma_f32_16x16x32_bf16 v[32:35], v[156:159], v[198:201], v[32:35]
	v_mfma_f32_16x16x32_bf16 v[20:23], v[148:151], v[206:209], v[20:23]
	v_mfma_f32_16x16x32_bf16 v[16:19], v[156:159], v[206:209], v[16:19]
	v_mfma_f32_16x16x32_bf16 v[44:47], v[160:163], v[176:179], v[44:47]
	v_mfma_f32_16x16x32_bf16 v[40:43], v[168:171], v[176:179], v[40:43]
	v_mfma_f32_16x16x32_bf16 v[28:31], v[160:163], v[184:187], v[28:31]
	v_mfma_f32_16x16x32_bf16 v[24:27], v[168:171], v[184:187], v[24:27]
	v_mfma_f32_16x16x32_bf16 v[12:15], v[160:163], v[194:197], v[12:15]
	v_mfma_f32_16x16x32_bf16 v[8:11], v[168:171], v[194:197], v[8:11]
	v_mfma_f32_16x16x32_bf16 v[4:7], v[160:163], v[202:205], v[4:7]
	v_mfma_f32_16x16x32_bf16 v[0:3], v[168:171], v[202:205], v[0:3]
	v_mfma_f32_16x16x32_bf16 v[44:47], v[164:167], v[180:183], v[44:47]
	v_mfma_f32_16x16x32_bf16 v[40:43], v[172:175], v[180:183], v[40:43]
	v_mfma_f32_16x16x32_bf16 v[28:31], v[164:167], v[188:191], v[28:31]
	v_mfma_f32_16x16x32_bf16 v[24:27], v[172:175], v[188:191], v[24:27]
	v_mfma_f32_16x16x32_bf16 v[12:15], v[164:167], v[198:201], v[12:15]
	v_mfma_f32_16x16x32_bf16 v[8:11], v[172:175], v[198:201], v[8:11]
	v_mfma_f32_16x16x32_bf16 v[4:7], v[164:167], v[206:209], v[4:7]
	v_mfma_f32_16x16x32_bf16 v[0:3], v[172:175], v[206:209], v[0:3]
	s_setprio 0
	s_barrier
	s_add_i32 s38, s38, 2
	s_add_u32 s36, s36, 0x100
	s_addc_u32 s37, s37, 0
	s_cmpk_gt_u32 s38, 0x55
	s_mov_b64 s[12:13], s[14:15]
	s_cbranch_scc0 .LBB0_690
	s_and_b64 vcc, exec, s[4:5]
	s_cbranch_vccz .LBB0_693
	s_barrier
